# LDS bank conflicts: P2 weight-copy slices stored the 64x64 transpose tile with the 8 lanes of one column 544 words apart (8-way conflict on every transposed read); rows now stored at ((r&7)<<3)|(r>>3)
# baseline (speedup 1.0000x reference)
; #define LAS __attribute__((address_space(3)))
; #define LDS_WAIT() asm volatile("s_waitcnt lgkmcnt(0)" ::: "memory")
; __device__ __forceinline__ void p0_load(const P0Item& it, f32x4 (&w)[16], int lane) {
;     const unsigned voff = (unsigned)(((lane >> 4) * it.ldw + (lane & 15) * 4) * 4);
; #pragma unroll
;     for (int i = 0; i < 16; ++i) w[i] = __builtin_nontemporal_load((const f32x4*)((const char*)(it.src + (size_t)(4 * i) * it.ldw) + voff));
; __device__ __forceinline__ void p0_finish(const P0Item& it, const f32x4 (&w)[16], LAS float* scr, int lane) {
;     const int c4 = (lane & 15) * 4, kr = lane >> 4;
;     if (it.gain) { const unsigned goff = (unsigned)(kr * 4);
; #pragma unroll
;         for (int i = 0; i < 16; ++i) { const float g = *(const float*)((const char*)(it.gain + 4 * i) + goff); *(LAS f32x4*)(scr + (kr + 4 * i) * 68 + c4) = w[i] * g; } }
;     else {
; #pragma unroll
;         for (int i = 0; i < 16; ++i) *(LAS f32x4*)(scr + (kr + 4 * i) * 68 + c4) = w[i]; }
;     LDS_WAIT(); asm volatile("" ::: "memory");
;     const unsigned soff = (unsigned)(((lane >> 3) * it.K + 8 * (lane & 7)) * 2);
; #pragma unroll
;     for (int j = 0; j < 8; ++j) { const int n = (lane >> 3) + 8 * j, c = lane & 7; const LAS float* sp = scr + (8 * c) * 68 + n;
.LBB0_144:
	s_add_u32 s0, s78, 0x46000000
	s_addc_u32 s1, s79, 0
	v_writelane_b32 v254, s46, 8
	s_add_u32 s16, s78, 0x300000
	v_writelane_b32 v254, s0, 9
	s_addc_u32 s17, s79, 0
	s_nop 0
	v_writelane_b32 v254, s1, 10
	s_add_u32 s0, s78, 0x6800000
	v_writelane_b32 v254, s0, 11
	s_addc_u32 s0, s79, 0
	s_add_u32 s58, s78, 0x8800000
	s_addc_u32 s59, s79, 0
	s_add_u32 s14, s78, 0xc800000
	s_addc_u32 s15, s79, 0
	s_add_u32 s3, s78, 0xe800000
	s_addc_u32 s56, s79, 0
	v_writelane_b32 v254, s0, 12
	s_add_u32 s0, s78, 0x18800000
	s_addc_u32 s1, s79, 0
	s_add_u32 s74, s78, 0x26000000
	s_addc_u32 s75, s79, 0
	s_add_u32 s90, s78, 0x2e000000
	s_addc_u32 s91, s79, 0
	s_add_u32 s83, s78, 0x3a000000
	s_addc_u32 s95, s79, 0
	v_writelane_b32 v254, s0, 13
	s_cmp_lt_i32 s96, 3
	s_nop 0
	v_writelane_b32 v254, s1, 14
	s_cselect_b64 s[0:1], -1, 0
	s_cmp_gt_i32 s97, 2
	s_cselect_b64 s[4:5], -1, 0
	s_and_b64 s[18:19], s[0:1], s[4:5]
	s_mov_b32 s0, s68
	v_writelane_b32 v254, s0, 15
	s_andn2_b64 vcc, exec, s[18:19]
	s_nop 0
	v_writelane_b32 v254, s1, 16
	v_writelane_b32 v254, s72, 17
	s_nop 1
	v_writelane_b32 v254, s73, 18
	v_writelane_b32 v254, s74, 19
	s_nop 1
	v_writelane_b32 v254, s75, 20
	s_cbranch_vccnz .LBB0_533
	s_add_u32 s20, s78, 0x100000
	s_addc_u32 s21, s79, 0
	s_add_u32 s33, s78, 0x10800000
	s_addc_u32 s60, s79, 0
	s_and_b32 s0, s2, 63
	s_mul_i32 s1, s0, 0x56
	s_lshr_b32 s1, s1, 8
	s_mul_i32 s1, s1, 3
	s_sub_i32 s0, s0, s1
	s_and_b32 s61, s0, 0xff
	s_cmp_lg_u32 s61, 0
	s_mov_b32 s26, 0
	s_cbranch_scc1 .LBB0_223
	v_mov_b32_e32 v134, v182
	v_readlane_b32 s24, v254, 8
	s_mov_b32 s25, s2
	v_mov_b64_e32 v[2:3], s[92:93]
	flat_load_dwordx2 v[138:139], v[2:3] offset:120 sc0 sc1
	s_waitcnt vmcnt(0)
	s_lshl_b32 s0, s24, 8
	s_add_i32 s10, s0, s25
	s_ashr_i32 s0, s10, 31
	s_lshr_b32 s0, s0, 24
	s_add_i32 s0, s10, s0
	s_ashr_i32 s1, s0, 8
	s_and_b32 s0, s0, 0x3ffff00
	s_sub_i32 s4, s10, s0
	s_lshl_b32 s0, s1, 6
	s_ashr_i32 s1, s0, 31
	flat_load_dwordx2 v[142:143], v[2:3] offset:112 sc0 sc1
	s_waitcnt vmcnt(0)
	v_lshlrev_b32_e32 v2, 4, v134
	s_lshl_b32 s8, s4, 6
	s_lshl_b64 s[4:5], s[0:1], 16
	v_ashrrev_i32_e32 v150, 4, v134
	v_and_b32_e32 v155, 0xf0, v2
	s_ashr_i32 s9, s8, 31
	v_mov_b32_e32 v141, 0
	v_lshl_or_b32 v140, v150, 16, v155
	s_mov_b32 s27, 0x40000
	s_mov_b32 s28, 0x80000
	s_mov_b32 s29, 0xc0000
	s_mov_b32 s30, 0x100000
	s_mov_b32 s31, 0x140000
	s_mov_b32 s34, 0x180000
	s_mov_b32 s35, 0x1c0000
	s_mov_b32 s36, 0x200000
	s_mov_b32 s37, 0x240000
	s_mov_b32 s38, 0x280000
	s_mov_b32 s39, 0x2c0000
	s_mov_b32 s40, 0x300000
	v_ashrrev_i32_e32 v152, 3, v134
	v_lshlrev_b32_e32 v136, 2, v150
	v_mov_b32_e32 v137, v141
	v_mov_b32_e32 v145, v141
	s_mov_b32 s42, 0x10000
	s_mov_b32 s43, 0x20000
	s_mov_b32 s44, 0x30000
	s_mov_b32 s45, 0x50000
	s_mov_b32 s46, 0x60000
	s_waitcnt lgkmcnt(0)
	v_lshl_add_u64 v[2:3], v[138:139], 0, s[4:5]
	v_lshl_add_u64 v[2:3], s[8:9], 2, v[2:3]
	v_lshl_add_u64 v[58:59], v[2:3], 0, v[140:141]
	v_add_co_u32_e32 v6, vcc, s27, v58
	s_mov_b32 s4, 0x340000
	s_nop 0
	v_addc_co_u32_e32 v7, vcc, 0, v59, vcc
	v_add_co_u32_e32 v10, vcc, s28, v58
	s_lshl_b64 s[8:9], s[8:9], 13
	s_nop 0
	v_addc_co_u32_e32 v11, vcc, 0, v59, vcc
	v_add_co_u32_e32 v14, vcc, s29, v58
	v_lshl_add_u64 v[66:67], s[0:1], 2, v[142:143]
	s_nop 0
	v_addc_co_u32_e32 v15, vcc, 0, v59, vcc
	v_add_co_u32_e32 v18, vcc, s30, v58
	v_cmp_eq_u64_e64 s[6:7], 0, v[142:143]
	s_nop 0
	v_addc_co_u32_e32 v19, vcc, 0, v59, vcc
	v_add_co_u32_e32 v22, vcc, s31, v58
	v_cndmask_b32_e64 v148, v66, 0, s[6:7]
	s_nop 0
	v_addc_co_u32_e32 v23, vcc, 0, v59, vcc
	v_add_co_u32_e32 v26, vcc, s34, v58
	v_cndmask_b32_e64 v149, v67, 0, s[6:7]
	s_nop 0
	v_addc_co_u32_e32 v27, vcc, 0, v59, vcc
	v_add_co_u32_e32 v30, vcc, s35, v58
	v_lshlrev_b32_e32 v67, 2, v152
	s_nop 0
	v_addc_co_u32_e32 v31, vcc, 0, v59, vcc
	v_add_co_u32_e32 v34, vcc, s36, v58
	v_lshl_add_u64 v[146:147], v[142:143], 0, v[136:137]
	s_nop 0
	v_addc_co_u32_e32 v35, vcc, 0, v59, vcc
	v_add_co_u32_e32 v38, vcc, s37, v58
	s_nop 1
	v_addc_co_u32_e32 v39, vcc, 0, v59, vcc
	v_add_co_u32_e32 v42, vcc, s38, v58
	flat_load_dwordx4 v[2:5], v[58:59] nt
	s_nop 0
	flat_load_dwordx4 v[6:9], v[6:7] nt
	s_nop 0
	flat_load_dwordx4 v[10:13], v[10:11] nt
	s_nop 0
	flat_load_dwordx4 v[14:17], v[14:15] nt
	s_nop 0
	flat_load_dwordx4 v[18:21], v[18:19] nt
	s_nop 0
	flat_load_dwordx4 v[22:25], v[22:23] nt
	s_nop 0
	flat_load_dwordx4 v[26:29], v[26:27] nt
	s_nop 0
	flat_load_dwordx4 v[30:33], v[30:31] nt
	s_nop 0
	flat_load_dwordx4 v[34:37], v[34:35] nt
	s_nop 0
	flat_load_dwordx4 v[38:41], v[38:39] nt
	v_addc_co_u32_e32 v43, vcc, 0, v59, vcc
	v_add_co_u32_e32 v46, vcc, s39, v58
	s_nop 1
	v_addc_co_u32_e32 v47, vcc, 0, v59, vcc
	v_add_co_u32_e32 v50, vcc, s40, v58
	flat_load_dwordx4 v[42:45], v[42:43] nt
	s_nop 0
	flat_load_dwordx4 v[46:49], v[46:47] nt
	v_addc_co_u32_e32 v51, vcc, 0, v59, vcc
	v_add_co_u32_e32 v54, vcc, s4, v58
	s_mov_b32 s4, 0x380000
	s_nop 0
	v_addc_co_u32_e32 v55, vcc, 0, v59, vcc
	v_add_co_u32_e32 v60, vcc, s4, v58
	s_mov_b32 s4, 0x3c0000
	s_nop 0
	v_addc_co_u32_e32 v61, vcc, 0, v59, vcc
	v_add_co_u32_e32 v62, vcc, s4, v58
	flat_load_dwordx4 v[50:53], v[50:51] nt
	s_nop 0
	flat_load_dwordx4 v[54:57], v[54:55] nt
	v_addc_co_u32_e32 v63, vcc, 0, v59, vcc
	flat_load_dwordx4 v[58:61], v[60:61] nt
	s_nop 0
	flat_load_dwordx4 v[62:65], v[62:63] nt
	s_mul_i32 s4, s24, 0x4400
	s_add_i32 s11, s4, 0
	s_add_u32 s8, s33, s8
	s_addc_u32 s9, s60, s9
	s_lshl_b64 s[0:1], s[0:1], 1
	s_add_u32 s0, s8, s0
	s_movk_i32 s8, 0x110
	v_mul_lo_u32 v66, v150, s8
	v_add3_u32 v151, s11, v155, v66
	v_mul_u32_u24_e32 v248, 0x770, v150
	v_add_u32_e32 v151, v151, v248
	v_lshlrev_b32_e32 v66, 3, v134
	v_and_b32_e32 v153, 56, v66
	v_lshlrev_b32_e32 v66, 13, v152
	v_lshl_or_b32 v144, v153, 1, v66
	v_mul_u32_u24_e32 v66, 0x110, v153
	v_cmp_ne_u64_e64 s[4:5], 0, v[142:143]
	s_addc_u32 s1, s9, s1
	v_add3_u32 v154, s11, v66, v67
	v_mul_u32_u24_e32 v248, 238, v153
	v_sub_u32_e32 v154, v154, v248
	s_add_i32 s41, s10, 0x1000
	s_branch .LBB0_148
; #define GAS __attribute__((address_space(1)))
; #define LAS __attribute__((address_space(3)))
; __device__ __forceinline__ unsigned cvt_pk_bf16(float lo, float hi) { unsigned r; asm volatile("v_cvt_pk_bf16_f32 %0, %1, %2" : "=v"(r) : "v"(lo), "v"(hi)); return r; }
; #define LDS_WAIT() asm volatile("s_waitcnt lgkmcnt(0)" ::: "memory")
; __device__ __forceinline__ void p0_finish(const P0Item& it, const f32x4 (&w)[16], LAS float* scr, int lane) {
;     const int c4 = (lane & 15) * 4, kr = lane >> 4;
;     if (it.gain) { const unsigned goff = (unsigned)(kr * 4);
; #pragma unroll
;         for (int i = 0; i < 16; ++i) { const float g = *(const float*)((const char*)(it.gain + 4 * i) + goff); *(LAS f32x4*)(scr + (kr + 4 * i) * 68 + c4) = w[i] * g; } }
;     else {
; #pragma unroll
;         for (int i = 0; i < 16; ++i) *(LAS f32x4*)(scr + (kr + 4 * i) * 68 + c4) = w[i]; }
;     LDS_WAIT(); asm volatile("" ::: "memory");
;     const unsigned soff = (unsigned)(((lane >> 3) * it.K + 8 * (lane & 7)) * 2);
; #pragma unroll
;     for (int j = 0; j < 8; ++j) { const int n = (lane >> 3) + 8 * j, c = lane & 7; const LAS float* sp = scr + (8 * c) * 68 + n;
;         u32x4 o; o.x = cvt_pk_bf16(sp[0 * 68], sp[1 * 68]); o.y = cvt_pk_bf16(sp[2 * 68], sp[3 * 68]); o.z = cvt_pk_bf16(sp[4 * 68], sp[5 * 68]); o.w = cvt_pk_bf16(sp[6 * 68], sp[7 * 68]);
;         *(GAS u32x4*)((char*)(it.dst + (size_t)(8 * j) * it.K) + soff) = o; }
;     LDS_WAIT(); asm volatile("" ::: "memory");
.LBB0_147:
	s_or_b64 exec, exec, s[22:23]
	s_waitcnt vmcnt(0)
	ds_write_b128 v151, v[66:69] offset:10608
	s_waitcnt lgkmcnt(0)
	s_lshl_b64 s[10:11], s[10:11], 13
	s_add_u32 s10, s33, s10
	ds_read_b32 v66, v154
	ds_read_b32 v67, v154 offset:2176
	s_addc_u32 s11, s60, s11
	s_lshl_b64 s[8:9], s[8:9], 1
	s_waitcnt lgkmcnt(0)
	v_cvt_pk_bf16_f32 v66, v66, v67
	ds_read_b32 v68, v154 offset:4352
	ds_read_b32 v69, v154 offset:6528
	s_add_u32 s8, s10, s8
	s_waitcnt lgkmcnt(0)
	v_cvt_pk_bf16_f32 v67, v68, v69
	ds_read_b32 v68, v154 offset:8704
	ds_read_b32 v69, v154 offset:10880
	s_addc_u32 s9, s11, s9
	s_waitcnt lgkmcnt(0)
	v_cvt_pk_bf16_f32 v68, v68, v69
	ds_read_b32 v70, v154 offset:13056
	ds_read_b32 v71, v154 offset:15232
	s_waitcnt lgkmcnt(0)
	v_cvt_pk_bf16_f32 v69, v70, v71
	v_lshl_add_u64 v[72:73], s[8:9], 0, v[144:145]
	ds_read_b32 v70, v154 offset:32
	ds_read_b32 v71, v154 offset:2208
	global_store_dwordx4 v[72:73], v[66:69], off
	v_add_co_u32_e32 v74, vcc, s42, v72
	s_waitcnt lgkmcnt(0)
	v_cvt_pk_bf16_f32 v66, v70, v71
	ds_read_b32 v68, v154 offset:4384
	ds_read_b32 v69, v154 offset:6560
	s_waitcnt lgkmcnt(0)
	v_cvt_pk_bf16_f32 v67, v68, v69
	ds_read_b32 v68, v154 offset:8736
	ds_read_b32 v69, v154 offset:10912
	s_waitcnt lgkmcnt(0)
	v_cvt_pk_bf16_f32 v68, v68, v69
	ds_read_b32 v70, v154 offset:13088
	ds_read_b32 v71, v154 offset:15264
	s_waitcnt lgkmcnt(0)
	v_cvt_pk_bf16_f32 v69, v70, v71
	v_addc_co_u32_e32 v75, vcc, 0, v73, vcc
	ds_read_b32 v70, v154 offset:64
	ds_read_b32 v71, v154 offset:2240
	global_store_dwordx4 v[74:75], v[66:69], off
	v_add_co_u32_e32 v74, vcc, s43, v72
	s_waitcnt lgkmcnt(0)
	v_cvt_pk_bf16_f32 v66, v70, v71
	ds_read_b32 v68, v154 offset:4416
	ds_read_b32 v69, v154 offset:6592
	s_waitcnt lgkmcnt(0)
	v_cvt_pk_bf16_f32 v67, v68, v69
	ds_read_b32 v68, v154 offset:8768
	ds_read_b32 v69, v154 offset:10944
	s_waitcnt lgkmcnt(0)
	v_cvt_pk_bf16_f32 v68, v68, v69
	ds_read_b32 v70, v154 offset:13120
	ds_read_b32 v71, v154 offset:15296
	s_waitcnt lgkmcnt(0)
	v_cvt_pk_bf16_f32 v69, v70, v71
	v_addc_co_u32_e32 v75, vcc, 0, v73, vcc
	ds_read_b32 v70, v154 offset:96
	ds_read_b32 v71, v154 offset:2272
	global_store_dwordx4 v[74:75], v[66:69], off
	v_add_co_u32_e32 v74, vcc, s44, v72
	s_waitcnt lgkmcnt(0)
	v_cvt_pk_bf16_f32 v66, v70, v71
	ds_read_b32 v68, v154 offset:4448
	ds_read_b32 v69, v154 offset:6624
	s_waitcnt lgkmcnt(0)
	v_cvt_pk_bf16_f32 v67, v68, v69
	ds_read_b32 v68, v154 offset:8800
	ds_read_b32 v69, v154 offset:10976
	s_waitcnt lgkmcnt(0)
	v_cvt_pk_bf16_f32 v68, v68, v69
	ds_read_b32 v70, v154 offset:13152
	ds_read_b32 v71, v154 offset:15328
	s_waitcnt lgkmcnt(0)
	v_cvt_pk_bf16_f32 v69, v70, v71
	v_addc_co_u32_e32 v75, vcc, 0, v73, vcc
	ds_read_b32 v70, v154 offset:128
	ds_read_b32 v71, v154 offset:2304
	global_store_dwordx4 v[74:75], v[66:69], off
	v_add_co_u32_e32 v74, vcc, s27, v72
	s_waitcnt lgkmcnt(0)
	v_cvt_pk_bf16_f32 v66, v70, v71
	ds_read_b32 v68, v154 offset:4480
	ds_read_b32 v69, v154 offset:6656
	s_waitcnt lgkmcnt(0)
	v_cvt_pk_bf16_f32 v67, v68, v69
	ds_read_b32 v68, v154 offset:8832
	ds_read_b32 v69, v154 offset:11008
	s_waitcnt lgkmcnt(0)
	v_cvt_pk_bf16_f32 v68, v68, v69
	ds_read_b32 v70, v154 offset:13184
	ds_read_b32 v71, v154 offset:15360
	s_waitcnt lgkmcnt(0)
	v_cvt_pk_bf16_f32 v69, v70, v71
	v_addc_co_u32_e32 v75, vcc, 0, v73, vcc
	ds_read_b32 v70, v154 offset:160
	ds_read_b32 v71, v154 offset:2336
	global_store_dwordx4 v[74:75], v[66:69], off
	v_add_co_u32_e32 v74, vcc, s45, v72
	s_waitcnt lgkmcnt(0)
	v_cvt_pk_bf16_f32 v66, v70, v71
	ds_read_b32 v68, v154 offset:4512
	ds_read_b32 v69, v154 offset:6688
	s_waitcnt lgkmcnt(0)
	v_cvt_pk_bf16_f32 v67, v68, v69
	ds_read_b32 v68, v154 offset:8864
	ds_read_b32 v69, v154 offset:11040
	s_waitcnt lgkmcnt(0)
	v_cvt_pk_bf16_f32 v68, v68, v69
	ds_read_b32 v70, v154 offset:13216
	ds_read_b32 v71, v154 offset:15392
	s_waitcnt lgkmcnt(0)
	v_cvt_pk_bf16_f32 v69, v70, v71
	v_addc_co_u32_e32 v75, vcc, 0, v73, vcc
	ds_read_b32 v70, v154 offset:192
	ds_read_b32 v71, v154 offset:2368
	global_store_dwordx4 v[74:75], v[66:69], off
	v_add_co_u32_e32 v74, vcc, s46, v72
	s_waitcnt lgkmcnt(0)
	v_cvt_pk_bf16_f32 v66, v70, v71
	ds_read_b32 v68, v154 offset:4544
	ds_read_b32 v69, v154 offset:6720
	s_waitcnt lgkmcnt(0)
	v_cvt_pk_bf16_f32 v67, v68, v69
	ds_read_b32 v68, v154 offset:8896
	ds_read_b32 v69, v154 offset:11072
	s_waitcnt lgkmcnt(0)
	v_cvt_pk_bf16_f32 v68, v68, v69
	ds_read_b32 v70, v154 offset:13248
	ds_read_b32 v71, v154 offset:15424
	s_waitcnt lgkmcnt(0)
	v_cvt_pk_bf16_f32 v69, v70, v71
	v_addc_co_u32_e32 v75, vcc, 0, v73, vcc
	ds_read_b32 v70, v154 offset:224
	ds_read_b32 v71, v154 offset:2400
	global_store_dwordx4 v[74:75], v[66:69], off
	v_add_co_u32_e32 v72, vcc, 0x70000, v72
	s_waitcnt lgkmcnt(0)
	v_cvt_pk_bf16_f32 v66, v70, v71
	ds_read_b32 v68, v154 offset:4576
	ds_read_b32 v69, v154 offset:6752
	s_waitcnt lgkmcnt(0)
	v_cvt_pk_bf16_f32 v67, v68, v69
	ds_read_b32 v68, v154 offset:8928
	ds_read_b32 v69, v154 offset:11104
	v_addc_co_u32_e32 v73, vcc, 0, v73, vcc
	s_waitcnt lgkmcnt(0)
	v_cvt_pk_bf16_f32 v68, v68, v69
	ds_read_b32 v70, v154 offset:13280
	ds_read_b32 v71, v154 offset:15456
	s_waitcnt lgkmcnt(0)
	v_cvt_pk_bf16_f32 v69, v70, v71
	global_store_dwordx4 v[72:73], v[66:69], off
	s_waitcnt lgkmcnt(0)
	s_add_i32 s26, s26, 2
	s_andn2_b64 vcc, exec, s[12:13]
	s_addk_i32 s41, 0x1000
	s_cbranch_vccz .LBB0_158
; #define LAS __attribute__((address_space(3)))
; __device__ __forceinline__ void p0_load(const P0Item& it, f32x4 (&w)[16], int lane) {
;     const unsigned voff = (unsigned)(((lane >> 4) * it.ldw + (lane & 15) * 4) * 4);
; #pragma unroll
;     for (int i = 0; i < 16; ++i) w[i] = __builtin_nontemporal_load((const f32x4*)((const char*)(it.src + (size_t)(4 * i) * it.ldw) + voff));
; }
; __device__ __forceinline__ void p0_finish(const P0Item& it, const f32x4 (&w)[16], LAS float* scr, int lane) {
;     const int c4 = (lane & 15) * 4, kr = lane >> 4;
;     if (it.gain) { const unsigned goff = (unsigned)(kr * 4);
; #pragma unroll
;         for (int i = 0; i < 16; ++i) { const float g = *(const float*)((const char*)(it.gain + 4 * i) + goff); *(LAS f32x4*)(scr + (kr + 4 * i) * 68 + c4) = w[i] * g; } }
.LBB0_148:
	s_add_i32 s8, s41, 0xfffff800
	s_ashr_i32 s9, s8, 31
	s_lshr_b32 s9, s9, 24
	s_add_i32 s9, s8, s9
	s_ashr_i32 s10, s9, 8
	s_and_b32 s9, s9, 0x3ffff00
	s_sub_i32 s9, s8, s9
	s_lshl_b32 s8, s10, 6
	s_lshl_b32 s10, s9, 6
	s_ashr_i32 s9, s8, 31
	s_lshl_b64 s[12:13], s[8:9], 16
	v_lshl_add_u64 v[66:67], v[138:139], 0, s[12:13]
	s_ashr_i32 s11, s10, 31
	v_lshl_add_u64 v[66:67], s[10:11], 2, v[66:67]
	v_lshl_add_u64 v[66:67], v[66:67], 0, v[140:141]
	v_add_co_u32_e32 v68, vcc, s27, v66
	s_nop 1
	v_addc_co_u32_e32 v69, vcc, 0, v67, vcc
	flat_load_dwordx4 v[126:129], v[66:67] nt
	flat_load_dwordx4 v[122:125], v[68:69] nt
	v_add_co_u32_e32 v68, vcc, s28, v66
	s_nop 1
	v_addc_co_u32_e32 v69, vcc, 0, v67, vcc
	v_add_co_u32_e32 v70, vcc, s29, v66
	s_nop 1
	v_addc_co_u32_e32 v71, vcc, 0, v67, vcc
	flat_load_dwordx4 v[118:121], v[68:69] nt
	flat_load_dwordx4 v[114:117], v[70:71] nt
	v_add_co_u32_e32 v68, vcc, s30, v66
	s_nop 1
	v_addc_co_u32_e32 v69, vcc, 0, v67, vcc
	v_add_co_u32_e32 v70, vcc, s31, v66
	s_nop 1
	v_addc_co_u32_e32 v71, vcc, 0, v67, vcc
	flat_load_dwordx4 v[110:113], v[68:69] nt
	flat_load_dwordx4 v[106:109], v[70:71] nt
	v_add_co_u32_e32 v68, vcc, s34, v66
	s_nop 1
	v_addc_co_u32_e32 v69, vcc, 0, v67, vcc
	v_add_co_u32_e32 v70, vcc, s35, v66
	s_nop 1
	v_addc_co_u32_e32 v71, vcc, 0, v67, vcc
	flat_load_dwordx4 v[102:105], v[68:69] nt
	flat_load_dwordx4 v[98:101], v[70:71] nt
	v_add_co_u32_e32 v68, vcc, s36, v66
	s_nop 1
	v_addc_co_u32_e32 v69, vcc, 0, v67, vcc
	v_add_co_u32_e32 v70, vcc, s37, v66
	s_nop 1
	v_addc_co_u32_e32 v71, vcc, 0, v67, vcc
	flat_load_dwordx4 v[94:97], v[68:69] nt
	flat_load_dwordx4 v[90:93], v[70:71] nt
	v_add_co_u32_e32 v68, vcc, s38, v66
	s_nop 1
	v_addc_co_u32_e32 v69, vcc, 0, v67, vcc
	v_add_co_u32_e32 v70, vcc, s39, v66
	s_nop 1
	v_addc_co_u32_e32 v71, vcc, 0, v67, vcc
	flat_load_dwordx4 v[86:89], v[68:69] nt
	flat_load_dwordx4 v[82:85], v[70:71] nt
	v_add_co_u32_e32 v68, vcc, s40, v66
	s_nop 1
	v_addc_co_u32_e32 v69, vcc, 0, v67, vcc
	v_add_co_u32_e32 v70, vcc, 0x340000, v66
	s_nop 1
	v_addc_co_u32_e32 v71, vcc, 0, v67, vcc
	flat_load_dwordx4 v[78:81], v[68:69] nt
	flat_load_dwordx4 v[74:77], v[70:71] nt
	v_add_co_u32_e32 v68, vcc, 0x380000, v66
	s_nop 1
	v_addc_co_u32_e32 v69, vcc, 0, v67, vcc
	v_add_co_u32_e32 v66, vcc, 0x3c0000, v66
	s_nop 1
	v_addc_co_u32_e32 v67, vcc, 0, v67, vcc
	flat_load_dwordx4 v[70:73], v[68:69] nt
	s_nop 0
	flat_load_dwordx4 v[66:69], v[66:67] nt
	v_cmp_ne_u64_e32 vcc, 0, v[148:149]
	s_and_saveexec_b64 s[12:13], vcc
	s_xor_b64 s[12:13], exec, s[12:13]
	s_cbranch_execz .LBB0_150
	v_lshl_add_u64 v[156:157], v[148:149], 0, v[136:137]
	global_load_dword v248, v[156:157], off
	global_load_dword v249, v[156:157], off offset:16
	global_load_dword v250, v[156:157], off offset:32
	global_load_dword v251, v[156:157], off offset:48
	global_load_dword v252, v[156:157], off offset:64
	global_load_dword v253, v[156:157], off offset:80
	s_waitcnt vmcnt(0) lgkmcnt(0)
	v_pk_mul_f32 v[132:133], v[4:5], v[248:249] op_sel_hi:[1,0]
	v_pk_mul_f32 v[130:131], v[2:3], v[248:249] op_sel_hi:[1,0]
	ds_write_b128 v151, v[130:133]
	s_nop 1
	v_pk_mul_f32 v[132:133], v[8:9], v[248:249] op_sel:[0,1]
	v_pk_mul_f32 v[130:131], v[6:7], v[248:249] op_sel:[0,1]
	ds_write_b128 v151, v[130:133] offset:8704
	s_nop 1
	v_pk_mul_f32 v[132:133], v[12:13], v[250:251] op_sel_hi:[1,0]
	v_pk_mul_f32 v[130:131], v[10:11], v[250:251] op_sel_hi:[1,0]
	ds_write_b128 v151, v[130:133] offset:272
	s_nop 1
	v_pk_mul_f32 v[132:133], v[16:17], v[250:251] op_sel:[0,1]
	v_pk_mul_f32 v[130:131], v[14:15], v[250:251] op_sel:[0,1]
	ds_write_b128 v151, v[130:133] offset:8976
	s_nop 1
	v_pk_mul_f32 v[132:133], v[20:21], v[252:253] op_sel_hi:[1,0]
	v_pk_mul_f32 v[130:131], v[18:19], v[252:253] op_sel_hi:[1,0]
	ds_write_b128 v151, v[130:133] offset:544
	s_nop 1
	v_pk_mul_f32 v[132:133], v[24:25], v[252:253] op_sel:[0,1]
	v_pk_mul_f32 v[130:131], v[22:23], v[252:253] op_sel:[0,1]
	ds_write_b128 v151, v[130:133] offset:9248
	s_nop 1
	global_load_dword v248, v[156:157], off offset:96
	global_load_dword v249, v[156:157], off offset:112
	global_load_dword v250, v[156:157], off offset:128
	global_load_dword v251, v[156:157], off offset:144
	global_load_dword v252, v[156:157], off offset:160
	global_load_dword v253, v[156:157], off offset:176
	s_waitcnt vmcnt(0) lgkmcnt(0)
	v_pk_mul_f32 v[132:133], v[28:29], v[248:249] op_sel_hi:[1,0]
	v_pk_mul_f32 v[130:131], v[26:27], v[248:249] op_sel_hi:[1,0]
	ds_write_b128 v151, v[130:133] offset:816
	s_nop 1
	v_pk_mul_f32 v[132:133], v[32:33], v[248:249] op_sel:[0,1]
	v_pk_mul_f32 v[130:131], v[30:31], v[248:249] op_sel:[0,1]
	ds_write_b128 v151, v[130:133] offset:9520
	s_nop 1
	v_pk_mul_f32 v[132:133], v[36:37], v[250:251] op_sel_hi:[1,0]
	v_pk_mul_f32 v[130:131], v[34:35], v[250:251] op_sel_hi:[1,0]
	ds_write_b128 v151, v[130:133] offset:1088
	s_nop 1
	v_pk_mul_f32 v[132:133], v[40:41], v[250:251] op_sel:[0,1]
	v_pk_mul_f32 v[130:131], v[38:39], v[250:251] op_sel:[0,1]
	ds_write_b128 v151, v[130:133] offset:9792
	s_nop 1
	v_pk_mul_f32 v[132:133], v[44:45], v[252:253] op_sel_hi:[1,0]
	v_pk_mul_f32 v[130:131], v[42:43], v[252:253] op_sel_hi:[1,0]
	ds_write_b128 v151, v[130:133] offset:1360
	s_nop 1
	v_pk_mul_f32 v[132:133], v[48:49], v[252:253] op_sel:[0,1]
	v_pk_mul_f32 v[130:131], v[46:47], v[252:253] op_sel:[0,1]
	ds_write_b128 v151, v[130:133] offset:10064
	s_nop 1
	global_load_dword v248, v[156:157], off offset:192
	global_load_dword v249, v[156:157], off offset:208
	global_load_dword v250, v[156:157], off offset:224
	global_load_dword v251, v[156:157], off offset:240
	s_waitcnt vmcnt(0) lgkmcnt(0)
	v_pk_mul_f32 v[132:133], v[52:53], v[248:249] op_sel_hi:[1,0]
	v_pk_mul_f32 v[130:131], v[50:51], v[248:249] op_sel_hi:[1,0]
	ds_write_b128 v151, v[130:133] offset:1632
	s_nop 1
	v_pk_mul_f32 v[132:133], v[56:57], v[248:249] op_sel:[0,1]
	v_pk_mul_f32 v[130:131], v[54:55], v[248:249] op_sel:[0,1]
	ds_write_b128 v151, v[130:133] offset:10336
	s_nop 1
	v_pk_mul_f32 v[132:133], v[60:61], v[250:251] op_sel_hi:[1,0]
	v_pk_mul_f32 v[130:131], v[58:59], v[250:251] op_sel_hi:[1,0]
	ds_write_b128 v151, v[130:133] offset:1904
	s_nop 1
	v_pk_mul_f32 v[132:133], v[64:65], v[250:251] op_sel:[0,1]
	v_pk_mul_f32 v[130:131], v[62:63], v[250:251] op_sel:[0,1]
; #define GAS __attribute__((address_space(1)))
; #define LAS __attribute__((address_space(3)))
; __device__ __forceinline__ unsigned cvt_pk_bf16(float lo, float hi) { unsigned r; asm volatile("v_cvt_pk_bf16_f32 %0, %1, %2" : "=v"(r) : "v"(lo), "v"(hi)); return r; }
; #define LDS_WAIT() asm volatile("s_waitcnt lgkmcnt(0)" ::: "memory")
; __device__ __forceinline__ void p0_finish(const P0Item& it, const f32x4 (&w)[16], LAS float* scr, int lane) {
;     const int c4 = (lane & 15) * 4, kr = lane >> 4;
;     if (it.gain) { const unsigned goff = (unsigned)(kr * 4);
; #pragma unroll
;         for (int i = 0; i < 16; ++i) { const float g = *(const float*)((const char*)(it.gain + 4 * i) + goff); *(LAS f32x4*)(scr + (kr + 4 * i) * 68 + c4) = w[i] * g; } }
;     else {
; #pragma unroll
;         for (int i = 0; i < 16; ++i) *(LAS f32x4*)(scr + (kr + 4 * i) * 68 + c4) = w[i]; }
;     LDS_WAIT(); asm volatile("" ::: "memory");
;     const unsigned soff = (unsigned)(((lane >> 3) * it.K + 8 * (lane & 7)) * 2);
; #pragma unroll
;     for (int j = 0; j < 8; ++j) { const int n = (lane >> 3) + 8 * j, c = lane & 7; const LAS float* sp = scr + (8 * c) * 68 + n;
;         u32x4 o; o.x = cvt_pk_bf16(sp[0 * 68], sp[1 * 68]); o.y = cvt_pk_bf16(sp[2 * 68], sp[3 * 68]); o.z = cvt_pk_bf16(sp[4 * 68], sp[5 * 68]); o.w = cvt_pk_bf16(sp[6 * 68], sp[7 * 68]);
;         *(GAS u32x4*)((char*)(it.dst + (size_t)(8 * j) * it.K) + soff) = o; }
;     LDS_WAIT(); asm volatile("" ::: "memory");
.LBB0_150:
	s_andn2_saveexec_b64 s[12:13], s[12:13]
	s_cbranch_execz .LBB0_152
	s_waitcnt vmcnt(0) lgkmcnt(0)
	v_mov_b64_e32 v[132:133], v[64:65]
	v_mov_b64_e32 v[130:131], v[62:63]
	ds_write_b128 v151, v[2:5]
	ds_write_b128 v151, v[6:9] offset:8704
	ds_write_b128 v151, v[10:13] offset:272
	ds_write_b128 v151, v[14:17] offset:8976
	ds_write_b128 v151, v[18:21] offset:544
	ds_write_b128 v151, v[22:25] offset:9248
	ds_write_b128 v151, v[26:29] offset:816
	ds_write_b128 v151, v[30:33] offset:9520
	ds_write_b128 v151, v[34:37] offset:1088
	ds_write_b128 v151, v[38:41] offset:9792
	ds_write_b128 v151, v[42:45] offset:1360
	ds_write_b128 v151, v[46:49] offset:10064
	ds_write_b128 v151, v[50:53] offset:1632
	ds_write_b128 v151, v[54:57] offset:10336
	ds_write_b128 v151, v[58:61] offset:1904
.LBB0_152:
	s_or_b64 exec, exec, s[12:13]
	ds_write_b128 v151, v[130:133] offset:10608
	s_waitcnt lgkmcnt(0)
	ds_read_b32 v130, v154
	ds_read_b32 v131, v154 offset:2176
	s_waitcnt lgkmcnt(0)
	v_cvt_pk_bf16_f32 v156, v130, v131
	ds_read_b32 v132, v154 offset:4352
	ds_read_b32 v133, v154 offset:6528
	v_add_u32_e32 v130, 0x400, v154
	s_waitcnt lgkmcnt(0)
	v_cvt_pk_bf16_f32 v157, v132, v133
	ds_read_b32 v132, v154 offset:8704
	ds_read_b32 v133, v154 offset:10880
	s_waitcnt lgkmcnt(0)
	v_cvt_pk_bf16_f32 v158, v132, v133
	ds_read_b32 v132, v154 offset:13056
	ds_read_b32 v133, v154 offset:15232
	s_waitcnt lgkmcnt(0)
	v_cvt_pk_bf16_f32 v159, v132, v133
	ds_read_b32 v132, v154 offset:32
	ds_read_b32 v133, v154 offset:2208
	v_lshl_add_u64 v[160:161], s[0:1], 0, v[144:145]
	global_store_dwordx4 v[160:161], v[156:159], off
	v_add_co_u32_e32 v162, vcc, s42, v160
	s_waitcnt lgkmcnt(0)
	v_cvt_pk_bf16_f32 v156, v132, v133
	ds_read_b32 v132, v154 offset:4384
	ds_read_b32 v133, v154 offset:6560
	s_waitcnt lgkmcnt(0)
	v_cvt_pk_bf16_f32 v157, v132, v133
	ds_read_b32 v132, v154 offset:8736
	ds_read_b32 v133, v154 offset:10912
	s_waitcnt lgkmcnt(0)
	v_cvt_pk_bf16_f32 v158, v132, v133
	ds_read_b32 v132, v154 offset:13088
	ds_read_b32 v133, v154 offset:15264
	s_waitcnt lgkmcnt(0)
	v_cvt_pk_bf16_f32 v159, v132, v133
	ds_read_b32 v132, v154 offset:64
	ds_read_b32 v133, v154 offset:2240
	v_addc_co_u32_e32 v163, vcc, 0, v161, vcc
	global_store_dwordx4 v[162:163], v[156:159], off
	v_add_co_u32_e32 v162, vcc, s43, v160
	s_waitcnt lgkmcnt(0)
	v_cvt_pk_bf16_f32 v156, v132, v133
	ds_read_b32 v132, v154 offset:4416
	ds_read_b32 v133, v154 offset:6592
	s_waitcnt lgkmcnt(0)
	v_cvt_pk_bf16_f32 v157, v132, v133
	ds_read_b32 v132, v154 offset:8768
	ds_read_b32 v133, v154 offset:10944
	s_waitcnt lgkmcnt(0)
	v_cvt_pk_bf16_f32 v158, v132, v133
	ds_read_b32 v132, v154 offset:13120
	ds_read_b32 v133, v154 offset:15296
	s_waitcnt lgkmcnt(0)
	v_cvt_pk_bf16_f32 v159, v132, v133
	ds_read_b32 v132, v154 offset:96
	ds_read_b32 v133, v154 offset:2272
	v_addc_co_u32_e32 v163, vcc, 0, v161, vcc
	global_store_dwordx4 v[162:163], v[156:159], off
	v_add_co_u32_e32 v162, vcc, s44, v160
	s_waitcnt lgkmcnt(0)
	v_cvt_pk_bf16_f32 v156, v132, v133
	ds_read_b32 v132, v154 offset:4448
	ds_read_b32 v133, v154 offset:6624
	s_waitcnt lgkmcnt(0)
	v_cvt_pk_bf16_f32 v157, v132, v133
	ds_read_b32 v132, v154 offset:8800
	ds_read_b32 v133, v154 offset:10976
	s_waitcnt lgkmcnt(0)
	v_cvt_pk_bf16_f32 v158, v132, v133
	ds_read_b32 v132, v154 offset:13152
	ds_read_b32 v133, v154 offset:15328
	s_waitcnt lgkmcnt(0)
	v_cvt_pk_bf16_f32 v159, v132, v133
	ds_read_b32 v132, v154 offset:128
	ds_read_b32 v133, v154 offset:2304
	v_addc_co_u32_e32 v163, vcc, 0, v161, vcc
	global_store_dwordx4 v[162:163], v[156:159], off
	v_add_co_u32_e32 v162, vcc, s27, v160
	s_waitcnt lgkmcnt(0)
	v_cvt_pk_bf16_f32 v156, v132, v133
	ds_read_b32 v132, v154 offset:4480
	ds_read_b32 v133, v154 offset:6656
	s_waitcnt lgkmcnt(0)
	v_cvt_pk_bf16_f32 v157, v132, v133
	ds_read_b32 v132, v154 offset:8832
	ds_read_b32 v133, v154 offset:11008
	s_waitcnt lgkmcnt(0)
	v_cvt_pk_bf16_f32 v158, v132, v133
	ds_read_b32 v132, v154 offset:13184
	ds_read_b32 v133, v154 offset:15360
	s_waitcnt lgkmcnt(0)
	v_cvt_pk_bf16_f32 v159, v132, v133
	ds_read_b32 v132, v154 offset:160
	ds_read_b32 v133, v154 offset:2336
	v_addc_co_u32_e32 v163, vcc, 0, v161, vcc
	global_store_dwordx4 v[162:163], v[156:159], off
	v_add_u32_e32 v131, 0x600, v154
	v_add_co_u32_e32 v162, vcc, s45, v160
	s_waitcnt lgkmcnt(0)
	v_cvt_pk_bf16_f32 v156, v132, v133
	ds_read_b32 v132, v154 offset:4512
	ds_read_b32 v133, v154 offset:6688
	s_waitcnt lgkmcnt(0)
	v_cvt_pk_bf16_f32 v157, v132, v133
	ds_read_b32 v132, v154 offset:8864
	ds_read_b32 v133, v154 offset:11040
	s_waitcnt lgkmcnt(0)
	v_cvt_pk_bf16_f32 v158, v132, v133
	ds_read_b32 v132, v154 offset:13216
	ds_read_b32 v133, v154 offset:15392
	s_waitcnt lgkmcnt(0)
	v_cvt_pk_bf16_f32 v159, v132, v133
	ds_read_b32 v132, v154 offset:192
	ds_read_b32 v133, v154 offset:2368
	v_addc_co_u32_e32 v163, vcc, 0, v161, vcc
	global_store_dwordx4 v[162:163], v[156:159], off
	v_add_co_u32_e32 v164, vcc, s46, v160
	s_waitcnt lgkmcnt(0)
	v_cvt_pk_bf16_f32 v156, v132, v133
	ds_read_b32 v132, v154 offset:4544
	ds_read_b32 v133, v154 offset:6720
	s_waitcnt lgkmcnt(0)
	v_cvt_pk_bf16_f32 v157, v132, v133
	ds_read_b32 v132, v154 offset:8896
	ds_read_b32 v133, v154 offset:11072
	s_waitcnt lgkmcnt(0)
	v_cvt_pk_bf16_f32 v158, v132, v133
	ds_read_b32 v162, v154 offset:13248
	ds_read_b32 v163, v154 offset:15424
	v_add_u32_e32 v132, 0x200, v154
	s_waitcnt lgkmcnt(0)
	v_cvt_pk_bf16_f32 v159, v162, v163
	v_addc_co_u32_e32 v165, vcc, 0, v161, vcc
	ds_read_b32 v162, v154 offset:224
	ds_read_b32 v163, v154 offset:2400
	global_store_dwordx4 v[164:165], v[156:159], off
	v_add_co_u32_e32 v160, vcc, 0x70000, v160
	s_waitcnt lgkmcnt(0)
	v_cvt_pk_bf16_f32 v156, v162, v163
	ds_read_b32 v158, v154 offset:4576
	ds_read_b32 v159, v154 offset:6752
	s_waitcnt lgkmcnt(0)
	v_cvt_pk_bf16_f32 v157, v158, v159
	ds_read_b32 v158, v154 offset:8928
	ds_read_b32 v159, v154 offset:11104
	v_addc_co_u32_e32 v161, vcc, 0, v161, vcc
	s_waitcnt lgkmcnt(0)
	v_cvt_pk_bf16_f32 v158, v158, v159
	ds_read_b32 v162, v154 offset:13280
	ds_read_b32 v163, v154 offset:15456
	s_waitcnt lgkmcnt(0)
	v_cvt_pk_bf16_f32 v159, v162, v163
	global_store_dwordx4 v[160:161], v[156:159], off
	s_waitcnt lgkmcnt(0)
	s_cmp_gt_u32 s26, 5
	s_cselect_b64 s[12:13], -1, 0
	s_and_b64 vcc, exec, s[12:13]
	s_cbranch_vccz .LBB0_155
	s_and_saveexec_b64 s[22:23], s[4:5]
	s_xor_b64 s[22:23], exec, s[22:23]
	s_cbranch_execnz .LBB0_156

; #define LAS __attribute__((address_space(3)))
; __device__ __forceinline__ void p0_finish(const P0Item& it, const f32x4 (&w)[16], LAS float* scr, int lane) {
;     const int c4 = (lane & 15) * 4, kr = lane >> 4;
;     if (it.gain) { const unsigned goff = (unsigned)(kr * 4);
; #pragma unroll
;         for (int i = 0; i < 16; ++i) { const float g = *(const float*)((const char*)(it.gain + 4 * i) + goff); *(LAS f32x4*)(scr + (kr + 4 * i) * 68 + c4) = w[i] * g; } }
;     else {
; #pragma unroll
;         for (int i = 0; i < 16; ++i) *(LAS f32x4*)(scr + (kr + 4 * i) * 68 + c4) = w[i]; }
.LBB0_156:
	v_lshl_add_u64 v[156:157], s[8:9], 2, v[146:147]
	global_load_dword v248, v[156:157], off
	global_load_dword v249, v[156:157], off offset:16
	global_load_dword v250, v[156:157], off offset:32
	global_load_dword v251, v[156:157], off offset:48
	global_load_dword v252, v[156:157], off offset:64
	global_load_dword v253, v[156:157], off offset:80
	s_waitcnt vmcnt(0) lgkmcnt(0)
	v_pk_mul_f32 v[128:129], v[128:129], v[248:249] op_sel_hi:[1,0]
	v_pk_mul_f32 v[126:127], v[126:127], v[248:249] op_sel_hi:[1,0]
	ds_write_b128 v151, v[126:129]
	s_nop 1
	v_pk_mul_f32 v[124:125], v[124:125], v[248:249] op_sel:[0,1]
	v_pk_mul_f32 v[122:123], v[122:123], v[248:249] op_sel:[0,1]
	ds_write_b128 v151, v[122:125] offset:8704
	s_nop 1
	v_pk_mul_f32 v[120:121], v[120:121], v[250:251] op_sel_hi:[1,0]
	v_pk_mul_f32 v[118:119], v[118:119], v[250:251] op_sel_hi:[1,0]
	ds_write_b128 v151, v[118:121] offset:272
	s_nop 1
	v_pk_mul_f32 v[116:117], v[116:117], v[250:251] op_sel:[0,1]
	v_pk_mul_f32 v[114:115], v[114:115], v[250:251] op_sel:[0,1]
	ds_write_b128 v151, v[114:117] offset:8976
	s_nop 1
	v_pk_mul_f32 v[112:113], v[112:113], v[252:253] op_sel_hi:[1,0]
	v_pk_mul_f32 v[110:111], v[110:111], v[252:253] op_sel_hi:[1,0]
	ds_write_b128 v151, v[110:113] offset:544
	s_nop 1
	v_pk_mul_f32 v[108:109], v[108:109], v[252:253] op_sel:[0,1]
	v_pk_mul_f32 v[106:107], v[106:107], v[252:253] op_sel:[0,1]
	ds_write_b128 v151, v[106:109] offset:9248
	s_nop 1
	global_load_dword v248, v[156:157], off offset:96
	global_load_dword v249, v[156:157], off offset:112
	global_load_dword v250, v[156:157], off offset:128
	global_load_dword v251, v[156:157], off offset:144
	global_load_dword v252, v[156:157], off offset:160
	global_load_dword v253, v[156:157], off offset:176
	s_waitcnt vmcnt(0) lgkmcnt(0)
	v_pk_mul_f32 v[104:105], v[104:105], v[248:249] op_sel_hi:[1,0]
	v_pk_mul_f32 v[102:103], v[102:103], v[248:249] op_sel_hi:[1,0]
	ds_write_b128 v151, v[102:105] offset:816
	s_nop 1
	v_pk_mul_f32 v[100:101], v[100:101], v[248:249] op_sel:[0,1]
	v_pk_mul_f32 v[98:99], v[98:99], v[248:249] op_sel:[0,1]
	ds_write_b128 v151, v[98:101] offset:9520
	s_nop 1
	v_pk_mul_f32 v[96:97], v[96:97], v[250:251] op_sel_hi:[1,0]
	v_pk_mul_f32 v[94:95], v[94:95], v[250:251] op_sel_hi:[1,0]
	ds_write_b128 v151, v[94:97] offset:1088
	s_nop 1
	v_pk_mul_f32 v[92:93], v[92:93], v[250:251] op_sel:[0,1]
	v_pk_mul_f32 v[90:91], v[90:91], v[250:251] op_sel:[0,1]
	ds_write_b128 v151, v[90:93] offset:9792
	s_nop 1
	v_pk_mul_f32 v[88:89], v[88:89], v[252:253] op_sel_hi:[1,0]
	v_pk_mul_f32 v[86:87], v[86:87], v[252:253] op_sel_hi:[1,0]
	ds_write_b128 v151, v[86:89] offset:1360
	s_nop 1
	v_pk_mul_f32 v[84:85], v[84:85], v[252:253] op_sel:[0,1]
	v_pk_mul_f32 v[82:83], v[82:83], v[252:253] op_sel:[0,1]
	ds_write_b128 v151, v[82:85] offset:10064
	s_nop 1
	global_load_dword v248, v[156:157], off offset:192
	global_load_dword v249, v[156:157], off offset:208
	global_load_dword v250, v[156:157], off offset:224
	global_load_dword v251, v[156:157], off offset:240
	s_waitcnt vmcnt(0) lgkmcnt(0)
	v_pk_mul_f32 v[80:81], v[80:81], v[248:249] op_sel_hi:[1,0]
	v_pk_mul_f32 v[78:79], v[78:79], v[248:249] op_sel_hi:[1,0]
	ds_write_b128 v151, v[78:81] offset:1632
	s_nop 1
	v_pk_mul_f32 v[76:77], v[76:77], v[248:249] op_sel:[0,1]
	v_pk_mul_f32 v[74:75], v[74:75], v[248:249] op_sel:[0,1]
	ds_write_b128 v151, v[74:77] offset:10336
	s_nop 1
	v_pk_mul_f32 v[72:73], v[72:73], v[250:251] op_sel_hi:[1,0]
	v_pk_mul_f32 v[70:71], v[70:71], v[250:251] op_sel_hi:[1,0]
	ds_write_b128 v151, v[70:73] offset:1904
	s_nop 1
	v_pk_mul_f32 v[68:69], v[68:69], v[250:251] op_sel:[0,1]
	v_pk_mul_f32 v[66:67], v[66:67], v[250:251] op_sel:[0,1]
	s_andn2_saveexec_b64 s[22:23], s[22:23]
	s_cbranch_execz .LBB0_147
.LBB0_157:
	s_waitcnt vmcnt(0)
	ds_write_b128 v151, v[126:129]
	ds_write_b128 v151, v[122:125] offset:8704
	ds_write_b128 v151, v[118:121] offset:272
	ds_write_b128 v151, v[114:117] offset:8976
	ds_write_b128 v151, v[110:113] offset:544
	ds_write_b128 v151, v[106:109] offset:9248
	ds_write_b128 v151, v[102:105] offset:816
	ds_write_b128 v151, v[98:101] offset:9520
	ds_write_b128 v151, v[94:97] offset:1088
	ds_write_b128 v151, v[90:93] offset:9792
	ds_write_b128 v151, v[86:89] offset:1360
	ds_write_b128 v151, v[82:85] offset:10064
	ds_write_b128 v151, v[78:81] offset:1632
	ds_write_b128 v151, v[74:77] offset:10336
	ds_write_b128 v151, v[70:73] offset:1904
	s_branch .LBB0_147

; #define GAS __attribute__((address_space(1)))
; #define LAS __attribute__((address_space(3)))
; __device__ __forceinline__ unsigned cvt_pk_bf16(float lo, float hi) { unsigned r; asm volatile("v_cvt_pk_bf16_f32 %0, %1, %2" : "=v"(r) : "v"(lo), "v"(hi)); return r; }
; #define LDS_WAIT() asm volatile("s_waitcnt lgkmcnt(0)" ::: "memory")
; __device__ __forceinline__ void p0_finish(const P0Item& it, const f32x4 (&w)[16], LAS float* scr, int lane) {
;     ...
;     else {
; #pragma unroll
;         for (int i = 0; i < 16; ++i) *(LAS f32x4*)(scr + (kr + 4 * i) * 68 + c4) = w[i]; }
;     LDS_WAIT(); asm volatile("" ::: "memory");
;     const unsigned soff = (unsigned)(((lane >> 3) * it.K + 8 * (lane & 7)) * 2);
; #pragma unroll
;     for (int j = 0; j < 8; ++j) { const int n = (lane >> 3) + 8 * j, c = lane & 7; const LAS float* sp = scr + (8 * c) * 68 + n;
;         u32x4 o; o.x = cvt_pk_bf16(sp[0 * 68], sp[1 * 68]); o.y = cvt_pk_bf16(sp[2 * 68], sp[3 * 68]); o.z = cvt_pk_bf16(sp[4 * 68], sp[5 * 68]); o.w = cvt_pk_bf16(sp[6 * 68], sp[7 * 68]);
;         *(GAS u32x4*)((char*)(it.dst + (size_t)(8 * j) * it.K) + soff) = o; }
;     LDS_WAIT(); asm volatile("" ::: "memory");
.LBB0_182:
	ds_write_b128 v151, v[66:69]
	ds_write_b128 v151, v[70:73] offset:8704
	ds_write_b128 v151, v[74:77] offset:272
	ds_write_b128 v151, v[78:81] offset:8976
	ds_write_b128 v151, v[82:85] offset:544
	ds_write_b128 v151, v[86:89] offset:9248
	ds_write_b128 v151, v[90:93] offset:816
	ds_write_b128 v151, v[94:97] offset:9520
	ds_write_b128 v151, v[98:101] offset:1088
	ds_write_b128 v151, v[102:105] offset:9792
	ds_write_b128 v151, v[106:109] offset:1360
	ds_write_b128 v151, v[110:113] offset:10064
	ds_write_b128 v151, v[114:117] offset:1632
	ds_write_b128 v151, v[118:121] offset:10336
	ds_write_b128 v151, v[122:125] offset:1904
	ds_write_b128 v151, v[126:129] offset:10608
	s_waitcnt lgkmcnt(0)
	ds_read_b32 v66, v154
	ds_read_b32 v67, v154 offset:2176
	s_waitcnt lgkmcnt(0)
	v_cvt_pk_bf16_f32 v66, v66, v67
	ds_read_b32 v68, v154 offset:4352
	ds_read_b32 v69, v154 offset:6528
	v_mul_lo_u32 v72, s8, v152
	s_waitcnt lgkmcnt(0)
	v_cvt_pk_bf16_f32 v67, v68, v69
	ds_read_b32 v68, v154 offset:8704
	ds_read_b32 v69, v154 offset:10880
	v_or_b32_e32 v72, v72, v153
	s_waitcnt lgkmcnt(0)
	v_cvt_pk_bf16_f32 v68, v68, v69
	ds_read_b32 v70, v154 offset:13056
	ds_read_b32 v71, v154 offset:15232
	s_waitcnt lgkmcnt(0)
	v_cvt_pk_bf16_f32 v69, v70, v71
	v_lshlrev_b32_e32 v72, 1, v72
	s_mov_b32 s9, s1
	ds_read_b32 v70, v154 offset:32
	ds_read_b32 v71, v154 offset:2208
	global_store_dwordx4 v72, v[66:69], s[6:7]
	s_lshl_b64 s[8:9], s[8:9], 4
	s_add_u32 s6, s6, s8
	s_waitcnt lgkmcnt(0)
	v_cvt_pk_bf16_f32 v66, v70, v71
	ds_read_b32 v68, v154 offset:4384
	ds_read_b32 v69, v154 offset:6560
	s_waitcnt lgkmcnt(0)
	v_cvt_pk_bf16_f32 v67, v68, v69
	ds_read_b32 v68, v154 offset:8736
	ds_read_b32 v69, v154 offset:10912
	s_waitcnt lgkmcnt(0)
	v_cvt_pk_bf16_f32 v68, v68, v69
	ds_read_b32 v70, v154 offset:13088
	ds_read_b32 v71, v154 offset:15264
	s_waitcnt lgkmcnt(0)
	v_cvt_pk_bf16_f32 v69, v70, v71
	s_addc_u32 s7, s7, s9
	ds_read_b32 v70, v154 offset:64
	ds_read_b32 v71, v154 offset:2240
	global_store_dwordx4 v72, v[66:69], s[6:7]
	s_add_u32 s6, s6, s8
	s_addc_u32 s7, s7, s9
	s_waitcnt lgkmcnt(0)
	v_cvt_pk_bf16_f32 v66, v70, v71
	ds_read_b32 v68, v154 offset:4416
	ds_read_b32 v69, v154 offset:6592
	s_waitcnt lgkmcnt(0)
	v_cvt_pk_bf16_f32 v67, v68, v69
	ds_read_b32 v68, v154 offset:8768
	ds_read_b32 v69, v154 offset:10944
	s_waitcnt lgkmcnt(0)
	v_cvt_pk_bf16_f32 v68, v68, v69
	ds_read_b32 v70, v154 offset:13120
	ds_read_b32 v71, v154 offset:15296
	s_waitcnt lgkmcnt(0)
	v_cvt_pk_bf16_f32 v69, v70, v71
	ds_read_b32 v70, v154 offset:96
	ds_read_b32 v71, v154 offset:2272
	global_store_dwordx4 v72, v[66:69], s[6:7]
	s_add_u32 s6, s6, s8
	s_addc_u32 s7, s7, s9
	s_waitcnt lgkmcnt(0)
	v_cvt_pk_bf16_f32 v66, v70, v71
	ds_read_b32 v68, v154 offset:4448
	ds_read_b32 v69, v154 offset:6624
	s_waitcnt lgkmcnt(0)
	v_cvt_pk_bf16_f32 v67, v68, v69
	ds_read_b32 v68, v154 offset:8800
	ds_read_b32 v69, v154 offset:10976
	s_waitcnt lgkmcnt(0)
	v_cvt_pk_bf16_f32 v68, v68, v69
	ds_read_b32 v70, v154 offset:13152
	ds_read_b32 v71, v154 offset:15328
	s_waitcnt lgkmcnt(0)
	v_cvt_pk_bf16_f32 v69, v70, v71
	ds_read_b32 v70, v154 offset:128
	ds_read_b32 v71, v154 offset:2304
	global_store_dwordx4 v72, v[66:69], s[6:7]
	s_add_u32 s6, s6, s8
	s_addc_u32 s7, s7, s9
	s_waitcnt lgkmcnt(0)
	v_cvt_pk_bf16_f32 v66, v70, v71
	ds_read_b32 v68, v154 offset:4480
	ds_read_b32 v69, v154 offset:6656
	s_waitcnt lgkmcnt(0)
	v_cvt_pk_bf16_f32 v67, v68, v69
	ds_read_b32 v68, v154 offset:8832
	ds_read_b32 v69, v154 offset:11008
	s_waitcnt lgkmcnt(0)
	v_cvt_pk_bf16_f32 v68, v68, v69
	ds_read_b32 v70, v154 offset:13184
	ds_read_b32 v71, v154 offset:15360
	s_waitcnt lgkmcnt(0)
	v_cvt_pk_bf16_f32 v69, v70, v71
	ds_read_b32 v70, v154 offset:160
	ds_read_b32 v71, v154 offset:2336
	global_store_dwordx4 v72, v[66:69], s[6:7]
	s_add_u32 s6, s6, s8
	s_addc_u32 s7, s7, s9
	s_waitcnt lgkmcnt(0)
	v_cvt_pk_bf16_f32 v66, v70, v71
	ds_read_b32 v68, v154 offset:4512
	ds_read_b32 v69, v154 offset:6688
	s_waitcnt lgkmcnt(0)
	v_cvt_pk_bf16_f32 v67, v68, v69
	ds_read_b32 v68, v154 offset:8864
	ds_read_b32 v69, v154 offset:11040
	s_waitcnt lgkmcnt(0)
	v_cvt_pk_bf16_f32 v68, v68, v69
	ds_read_b32 v70, v154 offset:13216
	ds_read_b32 v71, v154 offset:15392
	s_waitcnt lgkmcnt(0)
	v_cvt_pk_bf16_f32 v69, v70, v71
	ds_read_b32 v70, v154 offset:192
	ds_read_b32 v71, v154 offset:2368
	global_store_dwordx4 v72, v[66:69], s[6:7]
	s_add_u32 s6, s6, s8
	s_addc_u32 s7, s7, s9
	s_waitcnt lgkmcnt(0)
	v_cvt_pk_bf16_f32 v66, v70, v71
	ds_read_b32 v68, v154 offset:4544
	ds_read_b32 v69, v154 offset:6720
	s_waitcnt lgkmcnt(0)
	v_cvt_pk_bf16_f32 v67, v68, v69
	ds_read_b32 v68, v154 offset:8896
	ds_read_b32 v69, v154 offset:11072
	s_waitcnt lgkmcnt(0)
	v_cvt_pk_bf16_f32 v68, v68, v69
	ds_read_b32 v70, v154 offset:13248
	ds_read_b32 v71, v154 offset:15424
	s_waitcnt lgkmcnt(0)
	v_cvt_pk_bf16_f32 v69, v70, v71
	ds_read_b32 v70, v154 offset:224
	ds_read_b32 v71, v154 offset:2400
	global_store_dwordx4 v72, v[66:69], s[6:7]
	s_add_u32 s6, s6, s8
	s_addc_u32 s7, s7, s9
	s_waitcnt lgkmcnt(0)
	v_cvt_pk_bf16_f32 v66, v70, v71
	ds_read_b32 v68, v154 offset:4576
	ds_read_b32 v69, v154 offset:6752
	s_waitcnt lgkmcnt(0)
	v_cvt_pk_bf16_f32 v67, v68, v69
	ds_read_b32 v68, v154 offset:8928
	ds_read_b32 v69, v154 offset:11104
	s_waitcnt lgkmcnt(0)
	v_cvt_pk_bf16_f32 v68, v68, v69
	ds_read_b32 v70, v154 offset:13280
	ds_read_b32 v71, v154 offset:15456
	s_waitcnt lgkmcnt(0)
	v_cvt_pk_bf16_f32 v69, v70, v71
	global_store_dwordx4 v72, v[66:69], s[6:7]
	s_waitcnt lgkmcnt(0)
	s_add_i32 s26, s26, 2
	s_add_i32 s22, s22, 16
	s_andn2_b64 vcc, exec, s[10:11]
	s_addk_i32 s23, 0x400
	s_cbranch_vccz .LBB0_216

; #define GAS __attribute__((address_space(1)))
; #define LAS __attribute__((address_space(3)))
; __device__ __forceinline__ unsigned cvt_pk_bf16(float lo, float hi) { unsigned r; asm volatile("v_cvt_pk_bf16_f32 %0, %1, %2" : "=v"(r) : "v"(lo), "v"(hi)); return r; }
; #define LDS_WAIT() asm volatile("s_waitcnt lgkmcnt(0)" ::: "memory")
; __device__ __forceinline__ void p0_load(const P0Item& it, f32x4 (&w)[16], int lane) {
;     const unsigned voff = (unsigned)(((lane >> 4) * it.ldw + (lane & 15) * 4) * 4);
; #pragma unroll
;     for (int i = 0; i < 16; ++i) w[i] = __builtin_nontemporal_load((const f32x4*)((const char*)(it.src + (size_t)(4 * i) * it.ldw) + voff));
; }
; __device__ __forceinline__ void p0_finish(const P0Item& it, const f32x4 (&w)[16], LAS float* scr, int lane) {
;     const int c4 = (lane & 15) * 4, kr = lane >> 4;
;     if (it.gain) { const unsigned goff = (unsigned)(kr * 4);
; #pragma unroll
;         for (int i = 0; i < 16; ++i) { const float g = *(const float*)((const char*)(it.gain + 4 * i) + goff); *(LAS f32x4*)(scr + (kr + 4 * i) * 68 + c4) = w[i] * g; } }
;     else {
; #pragma unroll
;         for (int i = 0; i < 16; ++i) *(LAS f32x4*)(scr + (kr + 4 * i) * 68 + c4) = w[i]; }
;     LDS_WAIT(); asm volatile("" ::: "memory");
;     const unsigned soff = (unsigned)(((lane >> 3) * it.K + 8 * (lane & 7)) * 2);
; #pragma unroll
;     for (int j = 0; j < 8; ++j) { const int n = (lane >> 3) + 8 * j, c = lane & 7; const LAS float* sp = scr + (8 * c) * 68 + n;
;         u32x4 o; o.x = cvt_pk_bf16(sp[0 * 68], sp[1 * 68]); o.y = cvt_pk_bf16(sp[2 * 68], sp[3 * 68]); o.z = cvt_pk_bf16(sp[4 * 68], sp[5 * 68]); o.w = cvt_pk_bf16(sp[6 * 68], sp[7 * 68]);
;         *(GAS u32x4*)((char*)(it.dst + (size_t)(8 * j) * it.K) + soff) = o; }
;     LDS_WAIT(); asm volatile("" ::: "memory");
.LBB0_199:
	v_lshl_add_u64 v[122:123], v[66:67], 0, v[144:145]
	v_add_co_u32_e32 v70, vcc, 0x10000, v122
	v_add_u32_e32 v137, 0x400, v154
	s_nop 0
	v_addc_co_u32_e32 v71, vcc, 0, v123, vcc
	v_add_co_u32_e32 v74, vcc, 0x20000, v122
	flat_load_dwordx4 v[66:69], v[122:123] nt
	s_nop 0
	flat_load_dwordx4 v[70:73], v[70:71] nt
	v_addc_co_u32_e32 v75, vcc, 0, v123, vcc
	v_add_co_u32_e32 v78, vcc, 0x30000, v122
	v_mul_lo_u32 v155, s0, v152
	s_nop 0
	v_addc_co_u32_e32 v79, vcc, 0, v123, vcc
	v_add_co_u32_e32 v82, vcc, 0x40000, v122
	flat_load_dwordx4 v[74:77], v[74:75] nt
	s_nop 0
	flat_load_dwordx4 v[78:81], v[78:79] nt
	v_addc_co_u32_e32 v83, vcc, 0, v123, vcc
	v_add_co_u32_e32 v86, vcc, 0x50000, v122
	v_add_lshl_u32 v155, v155, v153, 1
	s_nop 0
	v_addc_co_u32_e32 v87, vcc, 0, v123, vcc
	v_add_co_u32_e32 v90, vcc, 0x60000, v122
	flat_load_dwordx4 v[82:85], v[82:83] nt
	s_nop 0
	flat_load_dwordx4 v[86:89], v[86:87] nt
	v_addc_co_u32_e32 v91, vcc, 0, v123, vcc
	v_add_co_u32_e32 v94, vcc, 0x70000, v122
	s_lshl_b64 s[10:11], s[0:1], 4
	s_nop 0
	v_addc_co_u32_e32 v95, vcc, 0, v123, vcc
	v_add_co_u32_e32 v98, vcc, 0x80000, v122
	flat_load_dwordx4 v[90:93], v[90:91] nt
	s_nop 0
	flat_load_dwordx4 v[94:97], v[94:95] nt
	v_addc_co_u32_e32 v99, vcc, 0, v123, vcc
	v_add_co_u32_e32 v102, vcc, 0x90000, v122
	s_add_u32 s12, s4, s10
	s_nop 0
	v_addc_co_u32_e32 v103, vcc, 0, v123, vcc
	v_add_co_u32_e32 v106, vcc, 0xa0000, v122
	flat_load_dwordx4 v[98:101], v[98:99] nt
	s_nop 0
	flat_load_dwordx4 v[102:105], v[102:103] nt
	v_addc_co_u32_e32 v107, vcc, 0, v123, vcc
	v_add_co_u32_e32 v110, vcc, 0xb0000, v122
	s_addc_u32 s13, s5, s11
	s_nop 0
	v_addc_co_u32_e32 v111, vcc, 0, v123, vcc
	v_add_co_u32_e32 v114, vcc, 0xc0000, v122
	flat_load_dwordx4 v[106:109], v[106:107] nt
	s_nop 0
	flat_load_dwordx4 v[110:113], v[110:111] nt
	v_addc_co_u32_e32 v115, vcc, 0, v123, vcc
	v_add_co_u32_e32 v118, vcc, 0xd0000, v122
	s_nop 1
	v_addc_co_u32_e32 v119, vcc, 0, v123, vcc
	v_add_co_u32_e32 v124, vcc, 0xe0000, v122
	flat_load_dwordx4 v[114:117], v[114:115] nt
	s_nop 0
	flat_load_dwordx4 v[118:121], v[118:119] nt
	v_addc_co_u32_e32 v125, vcc, 0, v123, vcc
	v_add_co_u32_e32 v126, vcc, 0xf0000, v122
	s_nop 1
	v_addc_co_u32_e32 v127, vcc, 0, v123, vcc
	flat_load_dwordx4 v[122:125], v[124:125] nt
	s_nop 0
	flat_load_dwordx4 v[126:129], v[126:127] nt
	s_waitcnt vmcnt(0) lgkmcnt(0)
	ds_write_b128 v151, v[2:5]
	ds_write_b128 v151, v[6:9] offset:8704
	ds_write_b128 v151, v[10:13] offset:272
	ds_write_b128 v151, v[14:17] offset:8976
	ds_write_b128 v151, v[18:21] offset:544
	ds_write_b128 v151, v[22:25] offset:9248
	ds_write_b128 v151, v[26:29] offset:816
	ds_write_b128 v151, v[30:33] offset:9520
	ds_write_b128 v151, v[34:37] offset:1088
	ds_write_b128 v151, v[38:41] offset:9792
	ds_write_b128 v151, v[42:45] offset:1360
	ds_write_b128 v151, v[46:49] offset:10064
	ds_write_b128 v151, v[50:53] offset:1632
	ds_write_b128 v151, v[54:57] offset:10336
	ds_write_b128 v151, v[58:61] offset:1904
	ds_write_b128 v151, v[62:65] offset:10608
	s_waitcnt lgkmcnt(0)
	ds_read_b32 v146, v154
	ds_read_b32 v147, v154 offset:2176
	s_waitcnt lgkmcnt(0)
	v_cvt_pk_bf16_f32 v146, v146, v147
	ds_read_b32 v148, v154 offset:4352
	ds_read_b32 v149, v154 offset:6528
	s_waitcnt lgkmcnt(0)
	v_cvt_pk_bf16_f32 v147, v148, v149
	ds_read_b32 v148, v154 offset:8704
	ds_read_b32 v149, v154 offset:10880
	s_waitcnt lgkmcnt(0)
	v_cvt_pk_bf16_f32 v148, v148, v149
	ds_read_b32 v156, v154 offset:13056
	ds_read_b32 v157, v154 offset:15232
	s_waitcnt lgkmcnt(0)
	v_cvt_pk_bf16_f32 v149, v156, v157
	ds_read_b32 v156, v154 offset:32
	ds_read_b32 v157, v154 offset:2208
	global_store_dwordx4 v155, v[146:149], s[4:5]
	s_waitcnt lgkmcnt(0)
	s_nop 0
	v_cvt_pk_bf16_f32 v146, v156, v157
	ds_read_b32 v148, v154 offset:4384
	ds_read_b32 v149, v154 offset:6560
	s_waitcnt lgkmcnt(0)
	v_cvt_pk_bf16_f32 v147, v148, v149
	ds_read_b32 v148, v154 offset:8736
	ds_read_b32 v149, v154 offset:10912
	s_waitcnt lgkmcnt(0)
	v_cvt_pk_bf16_f32 v148, v148, v149
	ds_read_b32 v156, v154 offset:13088
	ds_read_b32 v157, v154 offset:15264
	s_waitcnt lgkmcnt(0)
	v_cvt_pk_bf16_f32 v149, v156, v157
	ds_read_b32 v156, v154 offset:64
	ds_read_b32 v157, v154 offset:2240
	global_store_dwordx4 v155, v[146:149], s[12:13]
	s_add_u32 s12, s12, s10
	s_addc_u32 s13, s13, s11
	s_waitcnt lgkmcnt(0)
	v_cvt_pk_bf16_f32 v146, v156, v157
	ds_read_b32 v148, v154 offset:4416
	ds_read_b32 v149, v154 offset:6592
	s_waitcnt lgkmcnt(0)
; #define GAS __attribute__((address_space(1)))
; #define LAS __attribute__((address_space(3)))
; __device__ __forceinline__ unsigned cvt_pk_bf16(float lo, float hi) { unsigned r; asm volatile("v_cvt_pk_bf16_f32 %0, %1, %2" : "=v"(r) : "v"(lo), "v"(hi)); return r; }
; #define LDS_WAIT() asm volatile("s_waitcnt lgkmcnt(0)" ::: "memory")
; __device__ __forceinline__ void p0_finish(const P0Item& it, const f32x4 (&w)[16], LAS float* scr, int lane) {
;     ...
;     const unsigned soff = (unsigned)(((lane >> 3) * it.K + 8 * (lane & 7)) * 2);
; #pragma unroll
;     for (int j = 0; j < 8; ++j) { const int n = (lane >> 3) + 8 * j, c = lane & 7; const LAS float* sp = scr + (8 * c) * 68 + n;
;         u32x4 o; o.x = cvt_pk_bf16(sp[0 * 68], sp[1 * 68]); o.y = cvt_pk_bf16(sp[2 * 68], sp[3 * 68]); o.z = cvt_pk_bf16(sp[4 * 68], sp[5 * 68]); o.w = cvt_pk_bf16(sp[6 * 68], sp[7 * 68]);
;         *(GAS u32x4*)((char*)(it.dst + (size_t)(8 * j) * it.K) + soff) = o; }
;     LDS_WAIT(); asm volatile("" ::: "memory");
	v_cvt_pk_bf16_f32 v147, v148, v149
	ds_read_b32 v148, v154 offset:8768
	ds_read_b32 v149, v154 offset:10944
	s_waitcnt lgkmcnt(0)
	v_cvt_pk_bf16_f32 v148, v148, v149
	ds_read_b32 v156, v154 offset:13120
	ds_read_b32 v157, v154 offset:15296
	s_waitcnt lgkmcnt(0)
	v_cvt_pk_bf16_f32 v149, v156, v157
	ds_read_b32 v156, v154 offset:96
	ds_read_b32 v157, v154 offset:2272
	global_store_dwordx4 v155, v[146:149], s[12:13]
	s_add_u32 s12, s12, s10
	s_addc_u32 s13, s13, s11
	s_waitcnt lgkmcnt(0)
	v_cvt_pk_bf16_f32 v146, v156, v157
	ds_read_b32 v148, v154 offset:4448
	ds_read_b32 v149, v154 offset:6624
	s_waitcnt lgkmcnt(0)
	v_cvt_pk_bf16_f32 v147, v148, v149
	ds_read_b32 v148, v154 offset:8800
	ds_read_b32 v149, v154 offset:10976
	s_waitcnt lgkmcnt(0)
	v_cvt_pk_bf16_f32 v148, v148, v149
	ds_read_b32 v156, v154 offset:13152
	ds_read_b32 v157, v154 offset:15328
	s_waitcnt lgkmcnt(0)
	v_cvt_pk_bf16_f32 v149, v156, v157
	ds_read_b32 v156, v154 offset:128
	ds_read_b32 v157, v154 offset:2304
	global_store_dwordx4 v155, v[146:149], s[12:13]
	s_add_u32 s12, s12, s10
	s_addc_u32 s13, s13, s11
	s_waitcnt lgkmcnt(0)
	v_cvt_pk_bf16_f32 v146, v156, v157
	ds_read_b32 v148, v154 offset:4480
	ds_read_b32 v149, v154 offset:6656
	s_waitcnt lgkmcnt(0)
	v_cvt_pk_bf16_f32 v147, v148, v149
	ds_read_b32 v148, v154 offset:8832
	ds_read_b32 v149, v154 offset:11008
	s_waitcnt lgkmcnt(0)
	v_cvt_pk_bf16_f32 v148, v148, v149
	ds_read_b32 v156, v154 offset:13184
	ds_read_b32 v157, v154 offset:15360
	s_waitcnt lgkmcnt(0)
	v_cvt_pk_bf16_f32 v149, v156, v157
	ds_read_b32 v156, v154 offset:160
	ds_read_b32 v157, v154 offset:2336
	global_store_dwordx4 v155, v[146:149], s[12:13]
	s_waitcnt lgkmcnt(0)
	v_cvt_pk_bf16_f32 v156, v156, v157
	ds_read_b32 v146, v154 offset:4512
	ds_read_b32 v147, v154 offset:6688
	s_waitcnt lgkmcnt(0)
	v_cvt_pk_bf16_f32 v157, v146, v147
	ds_read_b32 v146, v154 offset:8864
	ds_read_b32 v147, v154 offset:11040
	s_waitcnt lgkmcnt(0)
	v_cvt_pk_bf16_f32 v158, v146, v147
	v_add_u32_e32 v146, 0x600, v154
	ds_read_b32 v148, v154 offset:13216
	ds_read_b32 v149, v154 offset:15392
	s_add_u32 s12, s12, s10
	s_waitcnt lgkmcnt(0)
	v_cvt_pk_bf16_f32 v159, v148, v149
	ds_read_b32 v148, v154 offset:192
	ds_read_b32 v149, v154 offset:2368
	s_addc_u32 s13, s13, s11
	global_store_dwordx4 v155, v[156:159], s[12:13]
	s_add_u32 s12, s12, s10
	s_addc_u32 s13, s13, s11
	s_waitcnt lgkmcnt(0)
	v_cvt_pk_bf16_f32 v156, v148, v149
	ds_read_b32 v148, v154 offset:4544
	ds_read_b32 v149, v154 offset:6720
	s_waitcnt lgkmcnt(0)
	v_cvt_pk_bf16_f32 v157, v148, v149
	ds_read_b32 v148, v154 offset:8896
	ds_read_b32 v149, v154 offset:11072
	s_waitcnt lgkmcnt(0)
	v_cvt_pk_bf16_f32 v158, v148, v149
	ds_read_b32 v148, v154 offset:13248
	ds_read_b32 v149, v154 offset:15424
	s_waitcnt lgkmcnt(0)
	v_cvt_pk_bf16_f32 v159, v148, v149
	ds_read_b32 v148, v154 offset:224
	ds_read_b32 v149, v154 offset:2400
	v_add_u32_e32 v147, 0x200, v154
	global_store_dwordx4 v155, v[156:159], s[12:13]
	s_add_u32 s10, s12, s10
	s_addc_u32 s11, s13, s11
	s_waitcnt lgkmcnt(0)
	v_cvt_pk_bf16_f32 v156, v148, v149
	ds_read_b32 v148, v154 offset:4576
	ds_read_b32 v149, v154 offset:6752
	s_waitcnt lgkmcnt(0)
	v_cvt_pk_bf16_f32 v157, v148, v149
	ds_read_b32 v148, v154 offset:8928
	ds_read_b32 v149, v154 offset:11104
	s_waitcnt lgkmcnt(0)
	v_cvt_pk_bf16_f32 v158, v148, v149
	ds_read_b32 v148, v154 offset:13280
	ds_read_b32 v149, v154 offset:15456
	s_waitcnt lgkmcnt(0)
	v_cvt_pk_bf16_f32 v159, v148, v149
	global_store_dwordx4 v155, v[156:159], s[10:11]
	s_waitcnt lgkmcnt(0)
	s_cmp_gt_u32 s26, 13
	s_cselect_b64 s[10:11], -1, 0
	s_and_b64 vcc, exec, s[10:11]
	s_cbranch_vccnz .LBB0_182
	s_add_i32 s9, s22, 0xffff1000
	s_cmpk_gt_i32 s9, 0xfff
	s_mov_b64 s[12:13], -1
	s_cbranch_scc0 .LBB0_214
	s_cmpk_gt_u32 s9, 0x1fff
	s_cbranch_scc0 .LBB0_211
	s_cmpk_gt_u32 s9, 0x2fff
	s_cbranch_scc0 .LBB0_208
	s_add_i32 s0, s23, 0x400
	s_and_b32 s27, s0, 0xfc0
	s_cmpk_gt_u32 s9, 0x3fff
	s_cbranch_scc0 .LBB0_205
	s_and_b32 s0, s9, 0x7fffffc0
	s_addk_i32 s0, 0xc000
	s_lshl_b64 s[4:5], s[0:1], 14
	v_lshl_add_u64 v[2:3], v[142:143], 0, s[4:5]
	s_lshl_b32 s4, s27, 2
	s_mov_b32 s5, s1
	v_lshl_add_u64 v[2:3], v[2:3], 0, s[4:5]
	s_lshl_b32 s4, s27, 15
	v_readlane_b32 s12, v254, 13
	v_readlane_b32 s13, v254, 14
	s_add_u32 s12, s12, s4
	s_addc_u32 s13, s13, 0
	s_lshl_b64 s[4:5], s[0:1], 1
	s_add_u32 s4, s12, s4
	s_addc_u32 s5, s13, s5
	s_mov_b64 s[12:13], 0

; #define LAS __attribute__((address_space(3)))
; #define LDS_WAIT() asm volatile("s_waitcnt lgkmcnt(0)" ::: "memory")
; __device__ __forceinline__ void p0_load(const P0Item& it, f32x4 (&w)[16], int lane) {
;     const unsigned voff = (unsigned)(((lane >> 4) * it.ldw + (lane & 15) * 4) * 4);
; #pragma unroll
;     for (int i = 0; i < 16; ++i) w[i] = __builtin_nontemporal_load((const f32x4*)((const char*)(it.src + (size_t)(4 * i) * it.ldw) + voff));
; }
; __device__ __forceinline__ void p0_finish(const P0Item& it, const f32x4 (&w)[16], LAS float* scr, int lane) {
;     const int c4 = (lane & 15) * 4, kr = lane >> 4;
;     if (it.gain) { const unsigned goff = (unsigned)(kr * 4);
; #pragma unroll
;         for (int i = 0; i < 16; ++i) { const float g = *(const float*)((const char*)(it.gain + 4 * i) + goff); *(LAS f32x4*)(scr + (kr + 4 * i) * 68 + c4) = w[i] * g; } }
;     else {
; #pragma unroll
;         for (int i = 0; i < 16; ++i) *(LAS f32x4*)(scr + (kr + 4 * i) * 68 + c4) = w[i]; }
;     LDS_WAIT(); asm volatile("" ::: "memory");
;     const unsigned soff = (unsigned)(((lane >> 3) * it.K + 8 * (lane & 7)) * 2);
.LBB0_257:
	s_cmp_lg_u32 s61, 1
	s_cbranch_scc1 .LBB0_335
	v_mov_b32_e32 v134, v182
	v_readlane_b32 s26, v254, 8
	s_mov_b32 s27, s2
	v_mov_b64_e32 v[2:3], s[92:93]
	flat_load_dwordx2 v[138:139], v[2:3] offset:120 sc0 sc1
	s_waitcnt vmcnt(0)
	s_lshl_b32 s0, s26, 8
	s_add_i32 s12, s0, s27
	s_ashr_i32 s0, s12, 31
	s_lshr_b32 s0, s0, 24
	s_add_i32 s0, s12, s0
	s_ashr_i32 s1, s0, 8
	s_and_b32 s0, s0, 0x3ffff00
	s_sub_i32 s6, s12, s0
	s_lshl_b32 s0, s1, 6
	s_ashr_i32 s1, s0, 31
	flat_load_dwordx2 v[142:143], v[2:3] offset:112 sc0 sc1
	s_waitcnt vmcnt(0)
	v_lshlrev_b32_e32 v2, 4, v134
	s_lshl_b32 s10, s6, 6
	s_lshl_b64 s[6:7], s[0:1], 16
	v_ashrrev_i32_e32 v150, 4, v134
	v_and_b32_e32 v156, 0xf0, v2
	s_ashr_i32 s11, s10, 31
	v_mov_b32_e32 v141, 0
	v_lshl_or_b32 v140, v150, 16, v156
	s_mov_b32 s28, 0x40000
	s_mov_b32 s29, 0x80000
	s_mov_b32 s30, 0xc0000
	s_mov_b32 s31, 0x100000
	s_mov_b32 s34, 0x140000
	s_mov_b32 s35, 0x180000
	s_mov_b32 s36, 0x1c0000
	s_mov_b32 s37, 0x200000
	s_mov_b32 s38, 0x240000
	s_mov_b32 s39, 0x280000
	s_mov_b32 s40, 0x2c0000
	s_mov_b32 s41, 0x300000
	v_ashrrev_i32_e32 v152, 3, v134
	v_lshlrev_b32_e32 v136, 2, v150
	v_mov_b32_e32 v137, v141
	s_mov_b32 s42, 0
	v_mov_b32_e32 v145, v141
	s_mov_b32 s44, 0x10000
	s_mov_b32 s45, 0x20000
	s_mov_b32 s46, 0x30000
	s_mov_b32 s47, 0x50000
	s_mov_b32 s48, 0x60000
	s_waitcnt lgkmcnt(0)
	v_lshl_add_u64 v[2:3], v[138:139], 0, s[6:7]
	v_lshl_add_u64 v[2:3], s[10:11], 2, v[2:3]
	v_lshl_add_u64 v[58:59], v[2:3], 0, v[140:141]
	v_add_co_u32_e32 v6, vcc, s28, v58
	s_mov_b32 s6, 0x340000
	s_nop 0
	v_addc_co_u32_e32 v7, vcc, 0, v59, vcc
	v_add_co_u32_e32 v10, vcc, s29, v58
	s_lshl_b64 s[10:11], s[10:11], 13
	s_nop 0
	v_addc_co_u32_e32 v11, vcc, 0, v59, vcc
	v_add_co_u32_e32 v14, vcc, s30, v58
	v_lshl_add_u64 v[66:67], s[0:1], 2, v[142:143]
	s_nop 0
	v_addc_co_u32_e32 v15, vcc, 0, v59, vcc
	v_add_co_u32_e32 v18, vcc, s31, v58
	v_cmp_eq_u64_e64 s[8:9], 0, v[142:143]
	s_nop 0
	v_addc_co_u32_e32 v19, vcc, 0, v59, vcc
	v_add_co_u32_e32 v22, vcc, s34, v58
	v_cndmask_b32_e64 v148, v66, 0, s[8:9]
	s_nop 0
	v_addc_co_u32_e32 v23, vcc, 0, v59, vcc
	v_add_co_u32_e32 v26, vcc, s35, v58
	v_cndmask_b32_e64 v149, v67, 0, s[8:9]
	s_nop 0
	v_addc_co_u32_e32 v27, vcc, 0, v59, vcc
	v_add_co_u32_e32 v30, vcc, s36, v58
	v_lshlrev_b32_e32 v67, 2, v152
	s_nop 0
	v_addc_co_u32_e32 v31, vcc, 0, v59, vcc
	v_add_co_u32_e32 v34, vcc, s37, v58
	v_lshl_add_u64 v[146:147], v[142:143], 0, v[136:137]
	s_nop 0
	v_addc_co_u32_e32 v35, vcc, 0, v59, vcc
	v_add_co_u32_e32 v38, vcc, s38, v58
	s_nop 1
	v_addc_co_u32_e32 v39, vcc, 0, v59, vcc
	v_add_co_u32_e32 v42, vcc, s39, v58
	flat_load_dwordx4 v[2:5], v[58:59] nt
	s_nop 0
	flat_load_dwordx4 v[6:9], v[6:7] nt
	s_nop 0
	flat_load_dwordx4 v[10:13], v[10:11] nt
	s_nop 0
	flat_load_dwordx4 v[14:17], v[14:15] nt
	s_nop 0
	flat_load_dwordx4 v[18:21], v[18:19] nt
	s_nop 0
	flat_load_dwordx4 v[22:25], v[22:23] nt
	s_nop 0
	flat_load_dwordx4 v[26:29], v[26:27] nt
	s_nop 0
	flat_load_dwordx4 v[30:33], v[30:31] nt
	s_nop 0
	flat_load_dwordx4 v[34:37], v[34:35] nt
	s_nop 0
	flat_load_dwordx4 v[38:41], v[38:39] nt
	v_addc_co_u32_e32 v43, vcc, 0, v59, vcc
	v_add_co_u32_e32 v46, vcc, s40, v58
	s_nop 1
	v_addc_co_u32_e32 v47, vcc, 0, v59, vcc
	v_add_co_u32_e32 v50, vcc, s41, v58
	flat_load_dwordx4 v[42:45], v[42:43] nt
	s_nop 0
	flat_load_dwordx4 v[46:49], v[46:47] nt
	v_addc_co_u32_e32 v51, vcc, 0, v59, vcc
	v_add_co_u32_e32 v54, vcc, s6, v58
	s_mov_b32 s6, 0x380000
	s_nop 0
	v_addc_co_u32_e32 v55, vcc, 0, v59, vcc
	v_add_co_u32_e32 v60, vcc, s6, v58
	s_mov_b32 s6, 0x3c0000
	s_nop 0
	v_addc_co_u32_e32 v61, vcc, 0, v59, vcc
	v_add_co_u32_e32 v62, vcc, s6, v58
	flat_load_dwordx4 v[50:53], v[50:51] nt
	s_nop 0
	flat_load_dwordx4 v[54:57], v[54:55] nt
	v_addc_co_u32_e32 v63, vcc, 0, v59, vcc
	flat_load_dwordx4 v[58:61], v[60:61] nt
	s_nop 0
	flat_load_dwordx4 v[62:65], v[62:63] nt
	s_mul_i32 s6, s26, 0x4400
	s_add_i32 s13, s6, 0
	s_add_u32 s10, s33, s10
	s_addc_u32 s11, s60, s11
	s_lshl_b64 s[0:1], s[0:1], 1
	s_add_u32 s0, s10, s0
	s_movk_i32 s10, 0x110
	v_mul_lo_u32 v66, v150, s10
	v_add3_u32 v151, s13, v156, v66
	v_mul_u32_u24_e32 v248, 0x770, v150
	v_add_u32_e32 v151, v151, v248
	v_lshlrev_b32_e32 v66, 3, v134
	v_and_b32_e32 v154, 56, v66
	v_lshlrev_b32_e32 v66, 13, v152
	v_lshl_or_b32 v144, v154, 1, v66
	v_mul_u32_u24_e32 v66, 0x110, v154
	v_cmp_ne_u64_e64 s[6:7], 0, v[142:143]
	s_addc_u32 s1, s11, s1
	v_add3_u32 v155, s13, v66, v67
	v_mul_u32_u24_e32 v248, 238, v154
	v_sub_u32_e32 v155, v155, v248
	s_add_i32 s43, s12, 0x1000
	s_branch .LBB0_260
; #define GAS __attribute__((address_space(1)))
; #define LAS __attribute__((address_space(3)))
; __device__ __forceinline__ unsigned cvt_pk_bf16(float lo, float hi) { unsigned r; asm volatile("v_cvt_pk_bf16_f32 %0, %1, %2" : "=v"(r) : "v"(lo), "v"(hi)); return r; }
; #define LDS_WAIT() asm volatile("s_waitcnt lgkmcnt(0)" ::: "memory")
; __device__ __forceinline__ void p0_finish(const P0Item& it, const f32x4 (&w)[16], LAS float* scr, int lane) {
;     ...
;         for (int i = 0; i < 16; ++i) *(LAS f32x4*)(scr + (kr + 4 * i) * 68 + c4) = w[i]; }
;     LDS_WAIT(); asm volatile("" ::: "memory");
;     const unsigned soff = (unsigned)(((lane >> 3) * it.K + 8 * (lane & 7)) * 2);
; #pragma unroll
;     for (int j = 0; j < 8; ++j) { const int n = (lane >> 3) + 8 * j, c = lane & 7; const LAS float* sp = scr + (8 * c) * 68 + n;
;         u32x4 o; o.x = cvt_pk_bf16(sp[0 * 68], sp[1 * 68]); o.y = cvt_pk_bf16(sp[2 * 68], sp[3 * 68]); o.z = cvt_pk_bf16(sp[4 * 68], sp[5 * 68]); o.w = cvt_pk_bf16(sp[6 * 68], sp[7 * 68]);
;         *(GAS u32x4*)((char*)(it.dst + (size_t)(8 * j) * it.K) + soff) = o; }
;     LDS_WAIT(); asm volatile("" ::: "memory");
.LBB0_259:
	s_or_b64 exec, exec, s[24:25]
	s_waitcnt vmcnt(0)
	ds_write_b128 v151, v[66:69] offset:10608
	s_waitcnt lgkmcnt(0)
	s_lshl_b64 s[12:13], s[12:13], 13
	s_add_u32 s12, s33, s12
	ds_read_b32 v66, v155
	ds_read_b32 v67, v155 offset:2176
	s_addc_u32 s13, s60, s13
	s_lshl_b64 s[10:11], s[10:11], 1
	s_waitcnt lgkmcnt(0)
	v_cvt_pk_bf16_f32 v66, v66, v67
	ds_read_b32 v68, v155 offset:4352
	ds_read_b32 v69, v155 offset:6528
	s_add_u32 s10, s12, s10
	s_waitcnt lgkmcnt(0)
	v_cvt_pk_bf16_f32 v67, v68, v69
	ds_read_b32 v68, v155 offset:8704
	ds_read_b32 v69, v155 offset:10880
	s_addc_u32 s11, s13, s11
	s_waitcnt lgkmcnt(0)
	v_cvt_pk_bf16_f32 v68, v68, v69
	ds_read_b32 v70, v155 offset:13056
	ds_read_b32 v71, v155 offset:15232
	s_waitcnt lgkmcnt(0)
	v_cvt_pk_bf16_f32 v69, v70, v71
	v_lshl_add_u64 v[72:73], s[10:11], 0, v[144:145]
	ds_read_b32 v70, v155 offset:32
	ds_read_b32 v71, v155 offset:2208
	global_store_dwordx4 v[72:73], v[66:69], off
	v_add_co_u32_e32 v74, vcc, s44, v72
	s_waitcnt lgkmcnt(0)
	v_cvt_pk_bf16_f32 v66, v70, v71
	ds_read_b32 v68, v155 offset:4384
	ds_read_b32 v69, v155 offset:6560
	s_waitcnt lgkmcnt(0)
	v_cvt_pk_bf16_f32 v67, v68, v69
	ds_read_b32 v68, v155 offset:8736
	ds_read_b32 v69, v155 offset:10912
	s_waitcnt lgkmcnt(0)
	v_cvt_pk_bf16_f32 v68, v68, v69
	ds_read_b32 v70, v155 offset:13088
	ds_read_b32 v71, v155 offset:15264
	s_waitcnt lgkmcnt(0)
	v_cvt_pk_bf16_f32 v69, v70, v71
	v_addc_co_u32_e32 v75, vcc, 0, v73, vcc
	ds_read_b32 v70, v155 offset:64
	ds_read_b32 v71, v155 offset:2240
	global_store_dwordx4 v[74:75], v[66:69], off
	v_add_co_u32_e32 v74, vcc, s45, v72
	s_waitcnt lgkmcnt(0)
	v_cvt_pk_bf16_f32 v66, v70, v71
	ds_read_b32 v68, v155 offset:4416
	ds_read_b32 v69, v155 offset:6592
	s_waitcnt lgkmcnt(0)
	v_cvt_pk_bf16_f32 v67, v68, v69
	ds_read_b32 v68, v155 offset:8768
	ds_read_b32 v69, v155 offset:10944
	s_waitcnt lgkmcnt(0)
	v_cvt_pk_bf16_f32 v68, v68, v69
	ds_read_b32 v70, v155 offset:13120
	ds_read_b32 v71, v155 offset:15296
	s_waitcnt lgkmcnt(0)
	v_cvt_pk_bf16_f32 v69, v70, v71
	v_addc_co_u32_e32 v75, vcc, 0, v73, vcc
	ds_read_b32 v70, v155 offset:96
	ds_read_b32 v71, v155 offset:2272
	global_store_dwordx4 v[74:75], v[66:69], off
	v_add_co_u32_e32 v74, vcc, s46, v72
	s_waitcnt lgkmcnt(0)
	v_cvt_pk_bf16_f32 v66, v70, v71
	ds_read_b32 v68, v155 offset:4448
	ds_read_b32 v69, v155 offset:6624
	s_waitcnt lgkmcnt(0)
	v_cvt_pk_bf16_f32 v67, v68, v69
	ds_read_b32 v68, v155 offset:8800
	ds_read_b32 v69, v155 offset:10976
	s_waitcnt lgkmcnt(0)
	v_cvt_pk_bf16_f32 v68, v68, v69
	ds_read_b32 v70, v155 offset:13152
	ds_read_b32 v71, v155 offset:15328
	s_waitcnt lgkmcnt(0)
	v_cvt_pk_bf16_f32 v69, v70, v71
	v_addc_co_u32_e32 v75, vcc, 0, v73, vcc
	ds_read_b32 v70, v155 offset:128
	ds_read_b32 v71, v155 offset:2304
	global_store_dwordx4 v[74:75], v[66:69], off
	v_add_co_u32_e32 v74, vcc, s28, v72
	s_waitcnt lgkmcnt(0)
	v_cvt_pk_bf16_f32 v66, v70, v71
	ds_read_b32 v68, v155 offset:4480
	ds_read_b32 v69, v155 offset:6656
	s_waitcnt lgkmcnt(0)
	v_cvt_pk_bf16_f32 v67, v68, v69
	ds_read_b32 v68, v155 offset:8832
	ds_read_b32 v69, v155 offset:11008
	s_waitcnt lgkmcnt(0)
	v_cvt_pk_bf16_f32 v68, v68, v69
	ds_read_b32 v70, v155 offset:13184
	ds_read_b32 v71, v155 offset:15360
	s_waitcnt lgkmcnt(0)
	v_cvt_pk_bf16_f32 v69, v70, v71
	v_addc_co_u32_e32 v75, vcc, 0, v73, vcc
	ds_read_b32 v70, v155 offset:160
	ds_read_b32 v71, v155 offset:2336
	global_store_dwordx4 v[74:75], v[66:69], off
	v_add_co_u32_e32 v74, vcc, s47, v72
	s_waitcnt lgkmcnt(0)
	v_cvt_pk_bf16_f32 v66, v70, v71
	ds_read_b32 v68, v155 offset:4512
	ds_read_b32 v69, v155 offset:6688
	s_waitcnt lgkmcnt(0)
	v_cvt_pk_bf16_f32 v67, v68, v69
	ds_read_b32 v68, v155 offset:8864
	ds_read_b32 v69, v155 offset:11040
	s_waitcnt lgkmcnt(0)
	v_cvt_pk_bf16_f32 v68, v68, v69
	ds_read_b32 v70, v155 offset:13216
	ds_read_b32 v71, v155 offset:15392
	s_waitcnt lgkmcnt(0)
	v_cvt_pk_bf16_f32 v69, v70, v71
	v_addc_co_u32_e32 v75, vcc, 0, v73, vcc
	ds_read_b32 v70, v155 offset:192
	ds_read_b32 v71, v155 offset:2368
	global_store_dwordx4 v[74:75], v[66:69], off
	v_add_co_u32_e32 v74, vcc, s48, v72
	s_waitcnt lgkmcnt(0)
	v_cvt_pk_bf16_f32 v66, v70, v71
	ds_read_b32 v68, v155 offset:4544
	ds_read_b32 v69, v155 offset:6720
	s_waitcnt lgkmcnt(0)
	v_cvt_pk_bf16_f32 v67, v68, v69
	ds_read_b32 v68, v155 offset:8896
	ds_read_b32 v69, v155 offset:11072
	s_waitcnt lgkmcnt(0)
	v_cvt_pk_bf16_f32 v68, v68, v69
	ds_read_b32 v70, v155 offset:13248
	ds_read_b32 v71, v155 offset:15424
	s_waitcnt lgkmcnt(0)
	v_cvt_pk_bf16_f32 v69, v70, v71
	v_addc_co_u32_e32 v75, vcc, 0, v73, vcc
	ds_read_b32 v70, v155 offset:224
	ds_read_b32 v71, v155 offset:2400
	global_store_dwordx4 v[74:75], v[66:69], off
	v_add_co_u32_e32 v72, vcc, 0x70000, v72
	s_waitcnt lgkmcnt(0)
	v_cvt_pk_bf16_f32 v66, v70, v71
	ds_read_b32 v68, v155 offset:4576
	ds_read_b32 v69, v155 offset:6752
	s_waitcnt lgkmcnt(0)
	v_cvt_pk_bf16_f32 v67, v68, v69
	ds_read_b32 v68, v155 offset:8928
	ds_read_b32 v69, v155 offset:11104
	v_addc_co_u32_e32 v73, vcc, 0, v73, vcc
	s_waitcnt lgkmcnt(0)
	v_cvt_pk_bf16_f32 v68, v68, v69
	ds_read_b32 v70, v155 offset:13280
	ds_read_b32 v71, v155 offset:15456
	s_waitcnt lgkmcnt(0)
	v_cvt_pk_bf16_f32 v69, v70, v71
	global_store_dwordx4 v[72:73], v[66:69], off
	s_waitcnt lgkmcnt(0)
	s_add_i32 s42, s42, 2
	s_andn2_b64 vcc, exec, s[22:23]
	s_addk_i32 s43, 0x1000
	s_cbranch_vccz .LBB0_270
; #define LAS __attribute__((address_space(3)))
; __device__ __forceinline__ void p0_load(const P0Item& it, f32x4 (&w)[16], int lane) {
;     const unsigned voff = (unsigned)(((lane >> 4) * it.ldw + (lane & 15) * 4) * 4);
; #pragma unroll
;     for (int i = 0; i < 16; ++i) w[i] = __builtin_nontemporal_load((const f32x4*)((const char*)(it.src + (size_t)(4 * i) * it.ldw) + voff));
; }
; __device__ __forceinline__ void p0_finish(const P0Item& it, const f32x4 (&w)[16], LAS float* scr, int lane) {
;     const int c4 = (lane & 15) * 4, kr = lane >> 4;
;     if (it.gain) { const unsigned goff = (unsigned)(kr * 4);
; #pragma unroll
;         for (int i = 0; i < 16; ++i) { const float g = *(const float*)((const char*)(it.gain + 4 * i) + goff); *(LAS f32x4*)(scr + (kr + 4 * i) * 68 + c4) = w[i] * g; } }
.LBB0_260:
	s_add_i32 s10, s43, 0xfffff800
	s_ashr_i32 s11, s10, 31
	s_lshr_b32 s11, s11, 24
	s_add_i32 s11, s10, s11
	s_ashr_i32 s12, s11, 8
	s_and_b32 s11, s11, 0x3ffff00
	s_sub_i32 s11, s10, s11
	s_lshl_b32 s10, s12, 6
	s_lshl_b32 s12, s11, 6
	s_ashr_i32 s11, s10, 31
	s_lshl_b64 s[22:23], s[10:11], 16
	v_lshl_add_u64 v[66:67], v[138:139], 0, s[22:23]
	s_ashr_i32 s13, s12, 31
	v_lshl_add_u64 v[66:67], s[12:13], 2, v[66:67]
	v_lshl_add_u64 v[66:67], v[66:67], 0, v[140:141]
	v_add_co_u32_e32 v68, vcc, s28, v66
	s_nop 1
	v_addc_co_u32_e32 v69, vcc, 0, v67, vcc
	flat_load_dwordx4 v[126:129], v[66:67] nt
	flat_load_dwordx4 v[122:125], v[68:69] nt
	v_add_co_u32_e32 v68, vcc, s29, v66
	s_nop 1
	v_addc_co_u32_e32 v69, vcc, 0, v67, vcc
	v_add_co_u32_e32 v70, vcc, s30, v66
	s_nop 1
	v_addc_co_u32_e32 v71, vcc, 0, v67, vcc
	flat_load_dwordx4 v[118:121], v[68:69] nt
	flat_load_dwordx4 v[114:117], v[70:71] nt
	v_add_co_u32_e32 v68, vcc, s31, v66
	s_nop 1
	v_addc_co_u32_e32 v69, vcc, 0, v67, vcc
	v_add_co_u32_e32 v70, vcc, s34, v66
	s_nop 1
	v_addc_co_u32_e32 v71, vcc, 0, v67, vcc
	flat_load_dwordx4 v[110:113], v[68:69] nt
	flat_load_dwordx4 v[106:109], v[70:71] nt
	v_add_co_u32_e32 v68, vcc, s35, v66
	s_nop 1
	v_addc_co_u32_e32 v69, vcc, 0, v67, vcc
	v_add_co_u32_e32 v70, vcc, s36, v66
	s_nop 1
	v_addc_co_u32_e32 v71, vcc, 0, v67, vcc
	flat_load_dwordx4 v[102:105], v[68:69] nt
	flat_load_dwordx4 v[98:101], v[70:71] nt
	v_add_co_u32_e32 v68, vcc, s37, v66
	s_nop 1
	v_addc_co_u32_e32 v69, vcc, 0, v67, vcc
	v_add_co_u32_e32 v70, vcc, s38, v66
	s_nop 1
	v_addc_co_u32_e32 v71, vcc, 0, v67, vcc
	flat_load_dwordx4 v[94:97], v[68:69] nt
	flat_load_dwordx4 v[90:93], v[70:71] nt
	v_add_co_u32_e32 v68, vcc, s39, v66
	s_nop 1
	v_addc_co_u32_e32 v69, vcc, 0, v67, vcc
	v_add_co_u32_e32 v70, vcc, s40, v66
	s_nop 1
	v_addc_co_u32_e32 v71, vcc, 0, v67, vcc
	flat_load_dwordx4 v[86:89], v[68:69] nt
	flat_load_dwordx4 v[82:85], v[70:71] nt
	v_add_co_u32_e32 v68, vcc, s41, v66
	s_nop 1
	v_addc_co_u32_e32 v69, vcc, 0, v67, vcc
	v_add_co_u32_e32 v70, vcc, 0x340000, v66
	s_nop 1
	v_addc_co_u32_e32 v71, vcc, 0, v67, vcc
	flat_load_dwordx4 v[78:81], v[68:69] nt
	flat_load_dwordx4 v[74:77], v[70:71] nt
	v_add_co_u32_e32 v68, vcc, 0x380000, v66
	s_nop 1
	v_addc_co_u32_e32 v69, vcc, 0, v67, vcc
	v_add_co_u32_e32 v66, vcc, 0x3c0000, v66
	s_nop 1
	v_addc_co_u32_e32 v67, vcc, 0, v67, vcc
	flat_load_dwordx4 v[70:73], v[68:69] nt
	s_nop 0
	flat_load_dwordx4 v[66:69], v[66:67] nt
	v_cmp_ne_u64_e32 vcc, 0, v[148:149]
	s_and_saveexec_b64 s[22:23], vcc
	s_xor_b64 s[22:23], exec, s[22:23]
	s_cbranch_execz .LBB0_262
	v_lshl_add_u64 v[164:165], v[148:149], 0, v[136:137]
	global_load_dword v248, v[164:165], off
	global_load_dword v249, v[164:165], off offset:16
	global_load_dword v250, v[164:165], off offset:32
	global_load_dword v251, v[164:165], off offset:48
	global_load_dword v252, v[164:165], off offset:64
	global_load_dword v253, v[164:165], off offset:80
	s_waitcnt vmcnt(0) lgkmcnt(0)
	v_pk_mul_f32 v[132:133], v[4:5], v[248:249] op_sel_hi:[1,0]
	v_pk_mul_f32 v[130:131], v[2:3], v[248:249] op_sel_hi:[1,0]
	ds_write_b128 v151, v[130:133]
	s_nop 1
	v_pk_mul_f32 v[132:133], v[8:9], v[248:249] op_sel:[0,1]
	v_pk_mul_f32 v[130:131], v[6:7], v[248:249] op_sel:[0,1]
	ds_write_b128 v151, v[130:133] offset:8704
	s_nop 1
	v_pk_mul_f32 v[132:133], v[12:13], v[250:251] op_sel_hi:[1,0]
	v_pk_mul_f32 v[130:131], v[10:11], v[250:251] op_sel_hi:[1,0]
	ds_write_b128 v151, v[130:133] offset:272
	s_nop 1
	v_pk_mul_f32 v[132:133], v[16:17], v[250:251] op_sel:[0,1]
	v_pk_mul_f32 v[130:131], v[14:15], v[250:251] op_sel:[0,1]
	ds_write_b128 v151, v[130:133] offset:8976
	s_nop 1
	v_pk_mul_f32 v[132:133], v[20:21], v[252:253] op_sel_hi:[1,0]
	v_pk_mul_f32 v[130:131], v[18:19], v[252:253] op_sel_hi:[1,0]
	ds_write_b128 v151, v[130:133] offset:544
	s_nop 1
	v_pk_mul_f32 v[132:133], v[24:25], v[252:253] op_sel:[0,1]
	v_pk_mul_f32 v[130:131], v[22:23], v[252:253] op_sel:[0,1]
	ds_write_b128 v151, v[130:133] offset:9248
	s_nop 1
	global_load_dword v248, v[164:165], off offset:96
	global_load_dword v249, v[164:165], off offset:112
	global_load_dword v250, v[164:165], off offset:128
	global_load_dword v251, v[164:165], off offset:144
	global_load_dword v252, v[164:165], off offset:160
	global_load_dword v253, v[164:165], off offset:176
	s_waitcnt vmcnt(0) lgkmcnt(0)
	v_pk_mul_f32 v[132:133], v[28:29], v[248:249] op_sel_hi:[1,0]
	v_pk_mul_f32 v[130:131], v[26:27], v[248:249] op_sel_hi:[1,0]
	ds_write_b128 v151, v[130:133] offset:816
	s_nop 1
	v_pk_mul_f32 v[132:133], v[32:33], v[248:249] op_sel:[0,1]
	v_pk_mul_f32 v[130:131], v[30:31], v[248:249] op_sel:[0,1]
	ds_write_b128 v151, v[130:133] offset:9520
	s_nop 1
	v_pk_mul_f32 v[132:133], v[36:37], v[250:251] op_sel_hi:[1,0]
	v_pk_mul_f32 v[130:131], v[34:35], v[250:251] op_sel_hi:[1,0]
	ds_write_b128 v151, v[130:133] offset:1088
	s_nop 1
	v_pk_mul_f32 v[132:133], v[40:41], v[250:251] op_sel:[0,1]
	v_pk_mul_f32 v[130:131], v[38:39], v[250:251] op_sel:[0,1]
	ds_write_b128 v151, v[130:133] offset:9792
	s_nop 1
	v_pk_mul_f32 v[132:133], v[44:45], v[252:253] op_sel_hi:[1,0]
	v_pk_mul_f32 v[130:131], v[42:43], v[252:253] op_sel_hi:[1,0]
	ds_write_b128 v151, v[130:133] offset:1360
	s_nop 1
	v_pk_mul_f32 v[132:133], v[48:49], v[252:253] op_sel:[0,1]
	v_pk_mul_f32 v[130:131], v[46:47], v[252:253] op_sel:[0,1]
	ds_write_b128 v151, v[130:133] offset:10064
	s_nop 1
	global_load_dword v248, v[164:165], off offset:192
	global_load_dword v249, v[164:165], off offset:208
	global_load_dword v250, v[164:165], off offset:224
	global_load_dword v251, v[164:165], off offset:240
	s_waitcnt vmcnt(0) lgkmcnt(0)
	v_pk_mul_f32 v[132:133], v[52:53], v[248:249] op_sel_hi:[1,0]
	v_pk_mul_f32 v[130:131], v[50:51], v[248:249] op_sel_hi:[1,0]
	ds_write_b128 v151, v[130:133] offset:1632
	s_nop 1
	v_pk_mul_f32 v[132:133], v[56:57], v[248:249] op_sel:[0,1]
	v_pk_mul_f32 v[130:131], v[54:55], v[248:249] op_sel:[0,1]
	ds_write_b128 v151, v[130:133] offset:10336
	s_nop 1
	v_pk_mul_f32 v[132:133], v[60:61], v[250:251] op_sel_hi:[1,0]
	v_pk_mul_f32 v[130:131], v[58:59], v[250:251] op_sel_hi:[1,0]
	ds_write_b128 v151, v[130:133] offset:1904
	s_nop 1
	v_pk_mul_f32 v[132:133], v[64:65], v[250:251] op_sel:[0,1]
	v_pk_mul_f32 v[130:131], v[62:63], v[250:251] op_sel:[0,1]
; #define GAS __attribute__((address_space(1)))
; #define LAS __attribute__((address_space(3)))
; __device__ __forceinline__ unsigned cvt_pk_bf16(float lo, float hi) { unsigned r; asm volatile("v_cvt_pk_bf16_f32 %0, %1, %2" : "=v"(r) : "v"(lo), "v"(hi)); return r; }
; #define LDS_WAIT() asm volatile("s_waitcnt lgkmcnt(0)" ::: "memory")
; __device__ __forceinline__ void p0_finish(const P0Item& it, const f32x4 (&w)[16], LAS float* scr, int lane) {
;     ...
;     else {
; #pragma unroll
;         for (int i = 0; i < 16; ++i) *(LAS f32x4*)(scr + (kr + 4 * i) * 68 + c4) = w[i]; }
;     LDS_WAIT(); asm volatile("" ::: "memory");
;     const unsigned soff = (unsigned)(((lane >> 3) * it.K + 8 * (lane & 7)) * 2);
; #pragma unroll
;     for (int j = 0; j < 8; ++j) { const int n = (lane >> 3) + 8 * j, c = lane & 7; const LAS float* sp = scr + (8 * c) * 68 + n;
;         u32x4 o; o.x = cvt_pk_bf16(sp[0 * 68], sp[1 * 68]); o.y = cvt_pk_bf16(sp[2 * 68], sp[3 * 68]); o.z = cvt_pk_bf16(sp[4 * 68], sp[5 * 68]); o.w = cvt_pk_bf16(sp[6 * 68], sp[7 * 68]);
;         *(GAS u32x4*)((char*)(it.dst + (size_t)(8 * j) * it.K) + soff) = o; }
;     LDS_WAIT(); asm volatile("" ::: "memory");
.LBB0_262:
	s_andn2_saveexec_b64 s[22:23], s[22:23]
	s_cbranch_execz .LBB0_264
	s_waitcnt vmcnt(0) lgkmcnt(0)
	v_mov_b64_e32 v[132:133], v[64:65]
	v_mov_b64_e32 v[130:131], v[62:63]
	ds_write_b128 v151, v[2:5]
	ds_write_b128 v151, v[6:9] offset:8704
	ds_write_b128 v151, v[10:13] offset:272
	ds_write_b128 v151, v[14:17] offset:8976
	ds_write_b128 v151, v[18:21] offset:544
	ds_write_b128 v151, v[22:25] offset:9248
	ds_write_b128 v151, v[26:29] offset:816
	ds_write_b128 v151, v[30:33] offset:9520
	ds_write_b128 v151, v[34:37] offset:1088
	ds_write_b128 v151, v[38:41] offset:9792
	ds_write_b128 v151, v[42:45] offset:1360
	ds_write_b128 v151, v[46:49] offset:10064
	ds_write_b128 v151, v[50:53] offset:1632
	ds_write_b128 v151, v[54:57] offset:10336
	ds_write_b128 v151, v[58:61] offset:1904
.LBB0_264:
	s_or_b64 exec, exec, s[22:23]
	ds_write_b128 v151, v[130:133] offset:10608
	s_waitcnt lgkmcnt(0)
	ds_read_b32 v130, v155
	ds_read_b32 v131, v155 offset:2176
	s_waitcnt lgkmcnt(0)
	v_cvt_pk_bf16_f32 v176, v130, v131
	ds_read_b32 v132, v155 offset:4352
	ds_read_b32 v133, v155 offset:6528
	v_add_u32_e32 v130, 0x400, v155
	s_waitcnt lgkmcnt(0)
	v_cvt_pk_bf16_f32 v177, v132, v133
	ds_read_b32 v132, v155 offset:8704
	ds_read_b32 v133, v155 offset:10880
	s_waitcnt lgkmcnt(0)
	v_cvt_pk_bf16_f32 v178, v132, v133
	ds_read_b32 v132, v155 offset:13056
	ds_read_b32 v133, v155 offset:15232
	s_waitcnt lgkmcnt(0)
	v_cvt_pk_bf16_f32 v179, v132, v133
	ds_read_b32 v132, v155 offset:32
	ds_read_b32 v133, v155 offset:2208
	v_lshl_add_u64 v[164:165], s[0:1], 0, v[144:145]
	global_store_dwordx4 v[164:165], v[176:179], off
	v_add_co_u32_e32 v180, vcc, s44, v164
	s_waitcnt lgkmcnt(0)
	v_cvt_pk_bf16_f32 v176, v132, v133
	ds_read_b32 v132, v155 offset:4384
	ds_read_b32 v133, v155 offset:6560
	s_waitcnt lgkmcnt(0)
	v_cvt_pk_bf16_f32 v177, v132, v133
	ds_read_b32 v132, v155 offset:8736
	ds_read_b32 v133, v155 offset:10912
	s_waitcnt lgkmcnt(0)
	v_cvt_pk_bf16_f32 v178, v132, v133
	ds_read_b32 v132, v155 offset:13088
	ds_read_b32 v133, v155 offset:15264
	s_waitcnt lgkmcnt(0)
	v_cvt_pk_bf16_f32 v179, v132, v133
	ds_read_b32 v132, v155 offset:64
	ds_read_b32 v133, v155 offset:2240
	v_addc_co_u32_e32 v181, vcc, 0, v165, vcc
	global_store_dwordx4 v[180:181], v[176:179], off
	v_add_co_u32_e32 v180, vcc, s45, v164
	s_waitcnt lgkmcnt(0)
	v_cvt_pk_bf16_f32 v176, v132, v133
	ds_read_b32 v132, v155 offset:4416
	ds_read_b32 v133, v155 offset:6592
	s_waitcnt lgkmcnt(0)
	v_cvt_pk_bf16_f32 v177, v132, v133
	ds_read_b32 v132, v155 offset:8768
	ds_read_b32 v133, v155 offset:10944
	s_waitcnt lgkmcnt(0)
	v_cvt_pk_bf16_f32 v178, v132, v133
	ds_read_b32 v132, v155 offset:13120
	ds_read_b32 v133, v155 offset:15296
	s_waitcnt lgkmcnt(0)
	v_cvt_pk_bf16_f32 v179, v132, v133
	ds_read_b32 v132, v155 offset:96
	ds_read_b32 v133, v155 offset:2272
	v_addc_co_u32_e32 v181, vcc, 0, v165, vcc
	global_store_dwordx4 v[180:181], v[176:179], off
	v_add_co_u32_e32 v180, vcc, s46, v164
	s_waitcnt lgkmcnt(0)
	v_cvt_pk_bf16_f32 v176, v132, v133
	ds_read_b32 v132, v155 offset:4448
	ds_read_b32 v133, v155 offset:6624
	s_waitcnt lgkmcnt(0)
	v_cvt_pk_bf16_f32 v177, v132, v133
	ds_read_b32 v132, v155 offset:8800
	ds_read_b32 v133, v155 offset:10976
	s_waitcnt lgkmcnt(0)
	v_cvt_pk_bf16_f32 v178, v132, v133
	ds_read_b32 v132, v155 offset:13152
	ds_read_b32 v133, v155 offset:15328
	s_waitcnt lgkmcnt(0)
	v_cvt_pk_bf16_f32 v179, v132, v133
	ds_read_b32 v132, v155 offset:128
	ds_read_b32 v133, v155 offset:2304
	v_addc_co_u32_e32 v181, vcc, 0, v165, vcc
	global_store_dwordx4 v[180:181], v[176:179], off
	v_add_co_u32_e32 v180, vcc, s28, v164
	s_waitcnt lgkmcnt(0)
	v_cvt_pk_bf16_f32 v176, v132, v133
	ds_read_b32 v132, v155 offset:4480
	ds_read_b32 v133, v155 offset:6656
	s_waitcnt lgkmcnt(0)
	v_cvt_pk_bf16_f32 v177, v132, v133
	ds_read_b32 v132, v155 offset:8832
	ds_read_b32 v133, v155 offset:11008
	s_waitcnt lgkmcnt(0)
	v_cvt_pk_bf16_f32 v178, v132, v133
	ds_read_b32 v132, v155 offset:13184
	ds_read_b32 v133, v155 offset:15360
	s_waitcnt lgkmcnt(0)
	v_cvt_pk_bf16_f32 v179, v132, v133
	ds_read_b32 v132, v155 offset:160
	ds_read_b32 v133, v155 offset:2336
	v_addc_co_u32_e32 v181, vcc, 0, v165, vcc
	global_store_dwordx4 v[180:181], v[176:179], off
	v_add_u32_e32 v131, 0x600, v155
	v_add_co_u32_e32 v180, vcc, s47, v164
	s_waitcnt lgkmcnt(0)
	v_cvt_pk_bf16_f32 v176, v132, v133
	ds_read_b32 v132, v155 offset:4512
	ds_read_b32 v133, v155 offset:6688
	s_waitcnt lgkmcnt(0)
	v_cvt_pk_bf16_f32 v177, v132, v133
	ds_read_b32 v132, v155 offset:8864
	ds_read_b32 v133, v155 offset:11040
	s_waitcnt lgkmcnt(0)
	v_cvt_pk_bf16_f32 v178, v132, v133
	ds_read_b32 v132, v155 offset:13216
	ds_read_b32 v133, v155 offset:15392
	s_waitcnt lgkmcnt(0)
	v_cvt_pk_bf16_f32 v179, v132, v133
	ds_read_b32 v132, v155 offset:192
	ds_read_b32 v133, v155 offset:2368
	v_addc_co_u32_e32 v181, vcc, 0, v165, vcc
	global_store_dwordx4 v[180:181], v[176:179], off
	v_add_co_u32_e32 v184, vcc, s48, v164
	s_waitcnt lgkmcnt(0)
	v_cvt_pk_bf16_f32 v176, v132, v133
	ds_read_b32 v132, v155 offset:4544
	ds_read_b32 v133, v155 offset:6720
	s_waitcnt lgkmcnt(0)
	v_cvt_pk_bf16_f32 v177, v132, v133
	ds_read_b32 v132, v155 offset:8896
	ds_read_b32 v133, v155 offset:11072
	s_waitcnt lgkmcnt(0)
	v_cvt_pk_bf16_f32 v178, v132, v133
	ds_read_b32 v180, v155 offset:13248
	ds_read_b32 v181, v155 offset:15424
	v_add_u32_e32 v132, 0x200, v155
	s_waitcnt lgkmcnt(0)
	v_cvt_pk_bf16_f32 v179, v180, v181
	v_addc_co_u32_e32 v185, vcc, 0, v165, vcc
	ds_read_b32 v180, v155 offset:224
	ds_read_b32 v181, v155 offset:2400
	global_store_dwordx4 v[184:185], v[176:179], off
	v_add_co_u32_e32 v164, vcc, 0x70000, v164
	s_waitcnt lgkmcnt(0)
	v_cvt_pk_bf16_f32 v176, v180, v181
	ds_read_b32 v178, v155 offset:4576
	ds_read_b32 v179, v155 offset:6752
	s_waitcnt lgkmcnt(0)
	v_cvt_pk_bf16_f32 v177, v178, v179
	ds_read_b32 v178, v155 offset:8928
	ds_read_b32 v179, v155 offset:11104
	v_addc_co_u32_e32 v165, vcc, 0, v165, vcc
	s_waitcnt lgkmcnt(0)
	v_cvt_pk_bf16_f32 v178, v178, v179
	ds_read_b32 v180, v155 offset:13280
	ds_read_b32 v181, v155 offset:15456
	s_waitcnt lgkmcnt(0)
	v_cvt_pk_bf16_f32 v179, v180, v181
	global_store_dwordx4 v[164:165], v[176:179], off
	s_waitcnt lgkmcnt(0)
	s_cmp_gt_u32 s42, 5
	s_cselect_b64 s[22:23], -1, 0
	s_and_b64 vcc, exec, s[22:23]
	s_cbranch_vccz .LBB0_267
	s_and_saveexec_b64 s[24:25], s[6:7]
	s_xor_b64 s[24:25], exec, s[24:25]
	s_cbranch_execnz .LBB0_268

; #define LAS __attribute__((address_space(3)))
; __device__ __forceinline__ void p0_finish(const P0Item& it, const f32x4 (&w)[16], LAS float* scr, int lane) {
;     const int c4 = (lane & 15) * 4, kr = lane >> 4;
;     if (it.gain) { const unsigned goff = (unsigned)(kr * 4);
; #pragma unroll
;         for (int i = 0; i < 16; ++i) { const float g = *(const float*)((const char*)(it.gain + 4 * i) + goff); *(LAS f32x4*)(scr + (kr + 4 * i) * 68 + c4) = w[i] * g; } }
.LBB0_268:
	v_lshl_add_u64 v[164:165], s[10:11], 2, v[146:147]
	global_load_dword v248, v[164:165], off
	global_load_dword v249, v[164:165], off offset:16
	global_load_dword v250, v[164:165], off offset:32
	global_load_dword v251, v[164:165], off offset:48
	global_load_dword v252, v[164:165], off offset:64
	global_load_dword v253, v[164:165], off offset:80
	s_waitcnt vmcnt(0) lgkmcnt(0)
	v_pk_mul_f32 v[128:129], v[128:129], v[248:249] op_sel_hi:[1,0]
	v_pk_mul_f32 v[126:127], v[126:127], v[248:249] op_sel_hi:[1,0]
	ds_write_b128 v151, v[126:129]
	s_nop 1
	v_pk_mul_f32 v[124:125], v[124:125], v[248:249] op_sel:[0,1]
	v_pk_mul_f32 v[122:123], v[122:123], v[248:249] op_sel:[0,1]
	ds_write_b128 v151, v[122:125] offset:8704
	s_nop 1
	v_pk_mul_f32 v[120:121], v[120:121], v[250:251] op_sel_hi:[1,0]
	v_pk_mul_f32 v[118:119], v[118:119], v[250:251] op_sel_hi:[1,0]
	ds_write_b128 v151, v[118:121] offset:272
	s_nop 1
	v_pk_mul_f32 v[116:117], v[116:117], v[250:251] op_sel:[0,1]
	v_pk_mul_f32 v[114:115], v[114:115], v[250:251] op_sel:[0,1]
	ds_write_b128 v151, v[114:117] offset:8976
	s_nop 1
	v_pk_mul_f32 v[112:113], v[112:113], v[252:253] op_sel_hi:[1,0]
	v_pk_mul_f32 v[110:111], v[110:111], v[252:253] op_sel_hi:[1,0]
	ds_write_b128 v151, v[110:113] offset:544
	s_nop 1
	v_pk_mul_f32 v[108:109], v[108:109], v[252:253] op_sel:[0,1]
	v_pk_mul_f32 v[106:107], v[106:107], v[252:253] op_sel:[0,1]
	ds_write_b128 v151, v[106:109] offset:9248
	s_nop 1
	global_load_dword v248, v[164:165], off offset:96
	global_load_dword v249, v[164:165], off offset:112
	global_load_dword v250, v[164:165], off offset:128
	global_load_dword v251, v[164:165], off offset:144
	global_load_dword v252, v[164:165], off offset:160
	global_load_dword v253, v[164:165], off offset:176
	s_waitcnt vmcnt(0) lgkmcnt(0)
	v_pk_mul_f32 v[104:105], v[104:105], v[248:249] op_sel_hi:[1,0]
	v_pk_mul_f32 v[102:103], v[102:103], v[248:249] op_sel_hi:[1,0]
	ds_write_b128 v151, v[102:105] offset:816
	s_nop 1
	v_pk_mul_f32 v[100:101], v[100:101], v[248:249] op_sel:[0,1]
	v_pk_mul_f32 v[98:99], v[98:99], v[248:249] op_sel:[0,1]
	ds_write_b128 v151, v[98:101] offset:9520
	s_nop 1
	v_pk_mul_f32 v[96:97], v[96:97], v[250:251] op_sel_hi:[1,0]
	v_pk_mul_f32 v[94:95], v[94:95], v[250:251] op_sel_hi:[1,0]
	ds_write_b128 v151, v[94:97] offset:1088
	s_nop 1
	v_pk_mul_f32 v[92:93], v[92:93], v[250:251] op_sel:[0,1]
	v_pk_mul_f32 v[90:91], v[90:91], v[250:251] op_sel:[0,1]
	ds_write_b128 v151, v[90:93] offset:9792
	s_nop 1
	v_pk_mul_f32 v[88:89], v[88:89], v[252:253] op_sel_hi:[1,0]
	v_pk_mul_f32 v[86:87], v[86:87], v[252:253] op_sel_hi:[1,0]
	ds_write_b128 v151, v[86:89] offset:1360
	s_nop 1
	v_pk_mul_f32 v[84:85], v[84:85], v[252:253] op_sel:[0,1]
	v_pk_mul_f32 v[82:83], v[82:83], v[252:253] op_sel:[0,1]
	ds_write_b128 v151, v[82:85] offset:10064
	s_nop 1
	global_load_dword v248, v[164:165], off offset:192
	global_load_dword v249, v[164:165], off offset:208
	global_load_dword v250, v[164:165], off offset:224
	global_load_dword v251, v[164:165], off offset:240
	s_waitcnt vmcnt(0) lgkmcnt(0)
	v_pk_mul_f32 v[80:81], v[80:81], v[248:249] op_sel_hi:[1,0]
	v_pk_mul_f32 v[78:79], v[78:79], v[248:249] op_sel_hi:[1,0]
	ds_write_b128 v151, v[78:81] offset:1632
	s_nop 1
	v_pk_mul_f32 v[76:77], v[76:77], v[248:249] op_sel:[0,1]
	v_pk_mul_f32 v[74:75], v[74:75], v[248:249] op_sel:[0,1]
	ds_write_b128 v151, v[74:77] offset:10336
	s_nop 1
	v_pk_mul_f32 v[72:73], v[72:73], v[250:251] op_sel_hi:[1,0]
	v_pk_mul_f32 v[70:71], v[70:71], v[250:251] op_sel_hi:[1,0]
	ds_write_b128 v151, v[70:73] offset:1904
	s_nop 1
	v_pk_mul_f32 v[68:69], v[68:69], v[250:251] op_sel:[0,1]
	v_pk_mul_f32 v[66:67], v[66:67], v[250:251] op_sel:[0,1]
	s_andn2_saveexec_b64 s[24:25], s[24:25]
	s_cbranch_execz .LBB0_259

; #define GAS __attribute__((address_space(1)))
; #define LAS __attribute__((address_space(3)))
; __device__ __forceinline__ unsigned cvt_pk_bf16(float lo, float hi) { unsigned r; asm volatile("v_cvt_pk_bf16_f32 %0, %1, %2" : "=v"(r) : "v"(lo), "v"(hi)); return r; }
; #define LDS_WAIT() asm volatile("s_waitcnt lgkmcnt(0)" ::: "memory")
; __device__ __forceinline__ void p0_finish(const P0Item& it, const f32x4 (&w)[16], LAS float* scr, int lane) {
;     ...
;     else {
; #pragma unroll
;         for (int i = 0; i < 16; ++i) *(LAS f32x4*)(scr + (kr + 4 * i) * 68 + c4) = w[i]; }
;     LDS_WAIT(); asm volatile("" ::: "memory");
;     const unsigned soff = (unsigned)(((lane >> 3) * it.K + 8 * (lane & 7)) * 2);
; #pragma unroll
;     for (int j = 0; j < 8; ++j) { const int n = (lane >> 3) + 8 * j, c = lane & 7; const LAS float* sp = scr + (8 * c) * 68 + n;
;         u32x4 o; o.x = cvt_pk_bf16(sp[0 * 68], sp[1 * 68]); o.y = cvt_pk_bf16(sp[2 * 68], sp[3 * 68]); o.z = cvt_pk_bf16(sp[4 * 68], sp[5 * 68]); o.w = cvt_pk_bf16(sp[6 * 68], sp[7 * 68]);
;         *(GAS u32x4*)((char*)(it.dst + (size_t)(8 * j) * it.K) + soff) = o; }
;     LDS_WAIT(); asm volatile("" ::: "memory");
.LBB0_294:
	ds_write_b128 v151, v[66:69]
	ds_write_b128 v151, v[70:73] offset:8704
	ds_write_b128 v151, v[74:77] offset:272
	ds_write_b128 v151, v[78:81] offset:8976
	ds_write_b128 v151, v[82:85] offset:544
	ds_write_b128 v151, v[86:89] offset:9248
	ds_write_b128 v151, v[90:93] offset:816
	ds_write_b128 v151, v[94:97] offset:9520
	ds_write_b128 v151, v[98:101] offset:1088
	ds_write_b128 v151, v[102:105] offset:9792
	ds_write_b128 v151, v[106:109] offset:1360
	ds_write_b128 v151, v[110:113] offset:10064
	ds_write_b128 v151, v[114:117] offset:1632
	ds_write_b128 v151, v[118:121] offset:10336
	ds_write_b128 v151, v[122:125] offset:1904
	ds_write_b128 v151, v[126:129] offset:10608
	s_waitcnt lgkmcnt(0)
	ds_read_b32 v66, v155
	ds_read_b32 v67, v155 offset:2176
	s_waitcnt lgkmcnt(0)
	v_cvt_pk_bf16_f32 v66, v66, v67
	ds_read_b32 v68, v155 offset:4352
	ds_read_b32 v69, v155 offset:6528
	v_mul_lo_u32 v72, s10, v152
	s_waitcnt lgkmcnt(0)
	v_cvt_pk_bf16_f32 v67, v68, v69
	ds_read_b32 v68, v155 offset:8704
	ds_read_b32 v69, v155 offset:10880
	v_or_b32_e32 v72, v72, v154
	s_waitcnt lgkmcnt(0)
	v_cvt_pk_bf16_f32 v68, v68, v69
	ds_read_b32 v70, v155 offset:13056
	ds_read_b32 v71, v155 offset:15232
	s_waitcnt lgkmcnt(0)
	v_cvt_pk_bf16_f32 v69, v70, v71
	v_lshlrev_b32_e32 v72, 1, v72
	s_mov_b32 s11, s1
	ds_read_b32 v70, v155 offset:32
	ds_read_b32 v71, v155 offset:2208
	global_store_dwordx4 v72, v[66:69], s[8:9]
	s_lshl_b64 s[10:11], s[10:11], 4
	s_add_u32 s8, s8, s10
	s_waitcnt lgkmcnt(0)
	v_cvt_pk_bf16_f32 v66, v70, v71
	ds_read_b32 v68, v155 offset:4384
	ds_read_b32 v69, v155 offset:6560
	s_waitcnt lgkmcnt(0)
	v_cvt_pk_bf16_f32 v67, v68, v69
	ds_read_b32 v68, v155 offset:8736
	ds_read_b32 v69, v155 offset:10912
	s_waitcnt lgkmcnt(0)
	v_cvt_pk_bf16_f32 v68, v68, v69
	ds_read_b32 v70, v155 offset:13088
	ds_read_b32 v71, v155 offset:15264
	s_waitcnt lgkmcnt(0)
	v_cvt_pk_bf16_f32 v69, v70, v71
	s_addc_u32 s9, s9, s11
	ds_read_b32 v70, v155 offset:64
	ds_read_b32 v71, v155 offset:2240
	global_store_dwordx4 v72, v[66:69], s[8:9]
	s_add_u32 s8, s8, s10
	s_addc_u32 s9, s9, s11
	s_waitcnt lgkmcnt(0)
	v_cvt_pk_bf16_f32 v66, v70, v71
	ds_read_b32 v68, v155 offset:4416
	ds_read_b32 v69, v155 offset:6592
	s_waitcnt lgkmcnt(0)
	v_cvt_pk_bf16_f32 v67, v68, v69
	ds_read_b32 v68, v155 offset:8768
	ds_read_b32 v69, v155 offset:10944
	s_waitcnt lgkmcnt(0)
	v_cvt_pk_bf16_f32 v68, v68, v69
	ds_read_b32 v70, v155 offset:13120
	ds_read_b32 v71, v155 offset:15296
	s_waitcnt lgkmcnt(0)
	v_cvt_pk_bf16_f32 v69, v70, v71
	ds_read_b32 v70, v155 offset:96
	ds_read_b32 v71, v155 offset:2272
	global_store_dwordx4 v72, v[66:69], s[8:9]
	s_add_u32 s8, s8, s10
	s_addc_u32 s9, s9, s11
	s_waitcnt lgkmcnt(0)
	v_cvt_pk_bf16_f32 v66, v70, v71
	ds_read_b32 v68, v155 offset:4448
	ds_read_b32 v69, v155 offset:6624
	s_waitcnt lgkmcnt(0)
	v_cvt_pk_bf16_f32 v67, v68, v69
	ds_read_b32 v68, v155 offset:8800
	ds_read_b32 v69, v155 offset:10976
	s_waitcnt lgkmcnt(0)
	v_cvt_pk_bf16_f32 v68, v68, v69
	ds_read_b32 v70, v155 offset:13152
	ds_read_b32 v71, v155 offset:15328
	s_waitcnt lgkmcnt(0)
	v_cvt_pk_bf16_f32 v69, v70, v71
	ds_read_b32 v70, v155 offset:128
	ds_read_b32 v71, v155 offset:2304
	global_store_dwordx4 v72, v[66:69], s[8:9]
	s_add_u32 s8, s8, s10
	s_addc_u32 s9, s9, s11
	s_waitcnt lgkmcnt(0)
	v_cvt_pk_bf16_f32 v66, v70, v71
	ds_read_b32 v68, v155 offset:4480
	ds_read_b32 v69, v155 offset:6656
	s_waitcnt lgkmcnt(0)
	v_cvt_pk_bf16_f32 v67, v68, v69
	ds_read_b32 v68, v155 offset:8832
	ds_read_b32 v69, v155 offset:11008
	s_waitcnt lgkmcnt(0)
	v_cvt_pk_bf16_f32 v68, v68, v69
	ds_read_b32 v70, v155 offset:13184
	ds_read_b32 v71, v155 offset:15360
	s_waitcnt lgkmcnt(0)
	v_cvt_pk_bf16_f32 v69, v70, v71
	ds_read_b32 v70, v155 offset:160
	ds_read_b32 v71, v155 offset:2336
	global_store_dwordx4 v72, v[66:69], s[8:9]
	s_add_u32 s8, s8, s10
	s_addc_u32 s9, s9, s11
	s_waitcnt lgkmcnt(0)
	v_cvt_pk_bf16_f32 v66, v70, v71
	ds_read_b32 v68, v155 offset:4512
	ds_read_b32 v69, v155 offset:6688
	s_waitcnt lgkmcnt(0)
	v_cvt_pk_bf16_f32 v67, v68, v69
	ds_read_b32 v68, v155 offset:8864
	ds_read_b32 v69, v155 offset:11040
	s_waitcnt lgkmcnt(0)
	v_cvt_pk_bf16_f32 v68, v68, v69
	ds_read_b32 v70, v155 offset:13216
	ds_read_b32 v71, v155 offset:15392
	s_waitcnt lgkmcnt(0)
	v_cvt_pk_bf16_f32 v69, v70, v71
	ds_read_b32 v70, v155 offset:192
	ds_read_b32 v71, v155 offset:2368
	global_store_dwordx4 v72, v[66:69], s[8:9]
	s_add_u32 s8, s8, s10
	s_addc_u32 s9, s9, s11
	s_waitcnt lgkmcnt(0)
	v_cvt_pk_bf16_f32 v66, v70, v71
	ds_read_b32 v68, v155 offset:4544
	ds_read_b32 v69, v155 offset:6720
	s_waitcnt lgkmcnt(0)
	v_cvt_pk_bf16_f32 v67, v68, v69
	ds_read_b32 v68, v155 offset:8896
	ds_read_b32 v69, v155 offset:11072
	s_waitcnt lgkmcnt(0)
	v_cvt_pk_bf16_f32 v68, v68, v69
	ds_read_b32 v70, v155 offset:13248
	ds_read_b32 v71, v155 offset:15424
	s_waitcnt lgkmcnt(0)
	v_cvt_pk_bf16_f32 v69, v70, v71
	ds_read_b32 v70, v155 offset:224
	ds_read_b32 v71, v155 offset:2400
	global_store_dwordx4 v72, v[66:69], s[8:9]
	s_add_u32 s8, s8, s10
	s_addc_u32 s9, s9, s11
	s_waitcnt lgkmcnt(0)
	v_cvt_pk_bf16_f32 v66, v70, v71
	ds_read_b32 v68, v155 offset:4576
	ds_read_b32 v69, v155 offset:6752
	s_waitcnt lgkmcnt(0)
	v_cvt_pk_bf16_f32 v67, v68, v69
	ds_read_b32 v68, v155 offset:8928
	ds_read_b32 v69, v155 offset:11104
	s_waitcnt lgkmcnt(0)
	v_cvt_pk_bf16_f32 v68, v68, v69
	ds_read_b32 v70, v155 offset:13280
	ds_read_b32 v71, v155 offset:15456
	s_waitcnt lgkmcnt(0)
	v_cvt_pk_bf16_f32 v69, v70, v71
	global_store_dwordx4 v72, v[66:69], s[8:9]
	s_waitcnt lgkmcnt(0)
	s_add_i32 s28, s28, 2
	s_add_i32 s24, s24, 16
	s_andn2_b64 vcc, exec, s[12:13]
	s_addk_i32 s25, 0x400
	s_cbranch_vccz .LBB0_328

; #define GAS __attribute__((address_space(1)))
; #define LAS __attribute__((address_space(3)))
; __device__ __forceinline__ unsigned cvt_pk_bf16(float lo, float hi) { unsigned r; asm volatile("v_cvt_pk_bf16_f32 %0, %1, %2" : "=v"(r) : "v"(lo), "v"(hi)); return r; }
; #define LDS_WAIT() asm volatile("s_waitcnt lgkmcnt(0)" ::: "memory")
; __device__ __forceinline__ void p0_load(const P0Item& it, f32x4 (&w)[16], int lane) {
;     const unsigned voff = (unsigned)(((lane >> 4) * it.ldw + (lane & 15) * 4) * 4);
; #pragma unroll
;     for (int i = 0; i < 16; ++i) w[i] = __builtin_nontemporal_load((const f32x4*)((const char*)(it.src + (size_t)(4 * i) * it.ldw) + voff));
; }
; __device__ __forceinline__ void p0_finish(const P0Item& it, const f32x4 (&w)[16], LAS float* scr, int lane) {
;     const int c4 = (lane & 15) * 4, kr = lane >> 4;
;     if (it.gain) { const unsigned goff = (unsigned)(kr * 4);
; #pragma unroll
;         for (int i = 0; i < 16; ++i) { const float g = *(const float*)((const char*)(it.gain + 4 * i) + goff); *(LAS f32x4*)(scr + (kr + 4 * i) * 68 + c4) = w[i] * g; } }
;     else {
; #pragma unroll
;         for (int i = 0; i < 16; ++i) *(LAS f32x4*)(scr + (kr + 4 * i) * 68 + c4) = w[i]; }
;     LDS_WAIT(); asm volatile("" ::: "memory");
;     const unsigned soff = (unsigned)(((lane >> 3) * it.K + 8 * (lane & 7)) * 2);
; #pragma unroll
;     for (int j = 0; j < 8; ++j) { const int n = (lane >> 3) + 8 * j, c = lane & 7; const LAS float* sp = scr + (8 * c) * 68 + n;
;         u32x4 o; o.x = cvt_pk_bf16(sp[0 * 68], sp[1 * 68]); o.y = cvt_pk_bf16(sp[2 * 68], sp[3 * 68]); o.z = cvt_pk_bf16(sp[4 * 68], sp[5 * 68]); o.w = cvt_pk_bf16(sp[6 * 68], sp[7 * 68]);
;         *(GAS u32x4*)((char*)(it.dst + (size_t)(8 * j) * it.K) + soff) = o; }
;     LDS_WAIT(); asm volatile("" ::: "memory");
.LBB0_311:
	v_lshl_add_u64 v[122:123], v[66:67], 0, v[144:145]
	v_add_co_u32_e32 v70, vcc, 0x10000, v122
	v_add_u32_e32 v137, 0x400, v155
	s_nop 0
	v_addc_co_u32_e32 v71, vcc, 0, v123, vcc
	v_add_co_u32_e32 v74, vcc, 0x20000, v122
	flat_load_dwordx4 v[66:69], v[122:123] nt
	s_nop 0
	flat_load_dwordx4 v[70:73], v[70:71] nt
	v_addc_co_u32_e32 v75, vcc, 0, v123, vcc
	v_add_co_u32_e32 v78, vcc, 0x30000, v122
	v_mul_lo_u32 v158, s0, v152
	s_nop 0
	v_addc_co_u32_e32 v79, vcc, 0, v123, vcc
	v_add_co_u32_e32 v82, vcc, 0x40000, v122
	flat_load_dwordx4 v[74:77], v[74:75] nt
	s_nop 0
	flat_load_dwordx4 v[78:81], v[78:79] nt
	v_addc_co_u32_e32 v83, vcc, 0, v123, vcc
	v_add_co_u32_e32 v86, vcc, 0x50000, v122
	v_add_lshl_u32 v158, v158, v154, 1
	s_nop 0
	v_addc_co_u32_e32 v87, vcc, 0, v123, vcc
	v_add_co_u32_e32 v90, vcc, 0x60000, v122
	flat_load_dwordx4 v[82:85], v[82:83] nt
	s_nop 0
	flat_load_dwordx4 v[86:89], v[86:87] nt
	v_addc_co_u32_e32 v91, vcc, 0, v123, vcc
	v_add_co_u32_e32 v94, vcc, 0x70000, v122
	s_lshl_b64 s[12:13], s[0:1], 4
	s_nop 0
	v_addc_co_u32_e32 v95, vcc, 0, v123, vcc
	v_add_co_u32_e32 v98, vcc, 0x80000, v122
	flat_load_dwordx4 v[90:93], v[90:91] nt
	s_nop 0
	flat_load_dwordx4 v[94:97], v[94:95] nt
	v_addc_co_u32_e32 v99, vcc, 0, v123, vcc
	v_add_co_u32_e32 v102, vcc, 0x90000, v122
	s_add_u32 s22, s6, s12
	s_nop 0
	v_addc_co_u32_e32 v103, vcc, 0, v123, vcc
	v_add_co_u32_e32 v106, vcc, 0xa0000, v122
	flat_load_dwordx4 v[98:101], v[98:99] nt
	s_nop 0
	flat_load_dwordx4 v[102:105], v[102:103] nt
	v_addc_co_u32_e32 v107, vcc, 0, v123, vcc
	v_add_co_u32_e32 v110, vcc, 0xb0000, v122
	s_addc_u32 s23, s7, s13
	s_nop 0
	v_addc_co_u32_e32 v111, vcc, 0, v123, vcc
	v_add_co_u32_e32 v114, vcc, 0xc0000, v122
	flat_load_dwordx4 v[106:109], v[106:107] nt
	s_nop 0
	flat_load_dwordx4 v[110:113], v[110:111] nt
	v_addc_co_u32_e32 v115, vcc, 0, v123, vcc
	v_add_co_u32_e32 v118, vcc, 0xd0000, v122
	s_nop 1
	v_addc_co_u32_e32 v119, vcc, 0, v123, vcc
	v_add_co_u32_e32 v124, vcc, 0xe0000, v122
	flat_load_dwordx4 v[114:117], v[114:115] nt
	s_nop 0
	flat_load_dwordx4 v[118:121], v[118:119] nt
	v_addc_co_u32_e32 v125, vcc, 0, v123, vcc
	v_add_co_u32_e32 v126, vcc, 0xf0000, v122
	s_nop 1
	v_addc_co_u32_e32 v127, vcc, 0, v123, vcc
	flat_load_dwordx4 v[122:125], v[124:125] nt
	s_nop 0
	flat_load_dwordx4 v[126:129], v[126:127] nt
	s_waitcnt vmcnt(0) lgkmcnt(0)
	ds_write_b128 v151, v[2:5]
	ds_write_b128 v151, v[6:9] offset:8704
	ds_write_b128 v151, v[10:13] offset:272
	ds_write_b128 v151, v[14:17] offset:8976
	ds_write_b128 v151, v[18:21] offset:544
	ds_write_b128 v151, v[22:25] offset:9248
	ds_write_b128 v151, v[26:29] offset:816
	ds_write_b128 v151, v[30:33] offset:9520
	ds_write_b128 v151, v[34:37] offset:1088
	ds_write_b128 v151, v[38:41] offset:9792
	ds_write_b128 v151, v[42:45] offset:1360
	ds_write_b128 v151, v[46:49] offset:10064
	ds_write_b128 v151, v[50:53] offset:1632
	ds_write_b128 v151, v[54:57] offset:10336
	ds_write_b128 v151, v[58:61] offset:1904
	ds_write_b128 v151, v[62:65] offset:10608
	s_waitcnt lgkmcnt(0)
	ds_read_b32 v146, v155
	ds_read_b32 v147, v155 offset:2176
	s_waitcnt lgkmcnt(0)
	v_cvt_pk_bf16_f32 v146, v146, v147
	ds_read_b32 v148, v155 offset:4352
	ds_read_b32 v149, v155 offset:6528
	s_waitcnt lgkmcnt(0)
	v_cvt_pk_bf16_f32 v147, v148, v149
	ds_read_b32 v148, v155 offset:8704
	ds_read_b32 v149, v155 offset:10880
	s_waitcnt lgkmcnt(0)
	v_cvt_pk_bf16_f32 v148, v148, v149
	ds_read_b32 v156, v155 offset:13056
	ds_read_b32 v157, v155 offset:15232
	s_waitcnt lgkmcnt(0)
	v_cvt_pk_bf16_f32 v149, v156, v157
	ds_read_b32 v156, v155 offset:32
	ds_read_b32 v157, v155 offset:2208
	global_store_dwordx4 v158, v[146:149], s[6:7]
	s_waitcnt lgkmcnt(0)
	s_nop 0
	v_cvt_pk_bf16_f32 v146, v156, v157
	ds_read_b32 v148, v155 offset:4384
	ds_read_b32 v149, v155 offset:6560
	s_waitcnt lgkmcnt(0)
	v_cvt_pk_bf16_f32 v147, v148, v149
	ds_read_b32 v148, v155 offset:8736
	ds_read_b32 v149, v155 offset:10912
	s_waitcnt lgkmcnt(0)
	v_cvt_pk_bf16_f32 v148, v148, v149
	ds_read_b32 v156, v155 offset:13088
	ds_read_b32 v157, v155 offset:15264
	s_waitcnt lgkmcnt(0)
	v_cvt_pk_bf16_f32 v149, v156, v157
	ds_read_b32 v156, v155 offset:64
	ds_read_b32 v157, v155 offset:2240
	global_store_dwordx4 v158, v[146:149], s[22:23]
	s_add_u32 s22, s22, s12
	s_addc_u32 s23, s23, s13
	s_waitcnt lgkmcnt(0)
	v_cvt_pk_bf16_f32 v146, v156, v157
	ds_read_b32 v148, v155 offset:4416
	ds_read_b32 v149, v155 offset:6592
	s_waitcnt lgkmcnt(0)
; #define GAS __attribute__((address_space(1)))
; #define LAS __attribute__((address_space(3)))
; __device__ __forceinline__ unsigned cvt_pk_bf16(float lo, float hi) { unsigned r; asm volatile("v_cvt_pk_bf16_f32 %0, %1, %2" : "=v"(r) : "v"(lo), "v"(hi)); return r; }
; #define LDS_WAIT() asm volatile("s_waitcnt lgkmcnt(0)" ::: "memory")
; __device__ __forceinline__ void p0_finish(const P0Item& it, const f32x4 (&w)[16], LAS float* scr, int lane) {
;     ...
;     const unsigned soff = (unsigned)(((lane >> 3) * it.K + 8 * (lane & 7)) * 2);
; #pragma unroll
;     for (int j = 0; j < 8; ++j) { const int n = (lane >> 3) + 8 * j, c = lane & 7; const LAS float* sp = scr + (8 * c) * 68 + n;
;         u32x4 o; o.x = cvt_pk_bf16(sp[0 * 68], sp[1 * 68]); o.y = cvt_pk_bf16(sp[2 * 68], sp[3 * 68]); o.z = cvt_pk_bf16(sp[4 * 68], sp[5 * 68]); o.w = cvt_pk_bf16(sp[6 * 68], sp[7 * 68]);
;         *(GAS u32x4*)((char*)(it.dst + (size_t)(8 * j) * it.K) + soff) = o; }
;     LDS_WAIT(); asm volatile("" ::: "memory");
	v_cvt_pk_bf16_f32 v147, v148, v149
	ds_read_b32 v148, v155 offset:8768
	ds_read_b32 v149, v155 offset:10944
	s_waitcnt lgkmcnt(0)
	v_cvt_pk_bf16_f32 v148, v148, v149
	ds_read_b32 v156, v155 offset:13120
	ds_read_b32 v157, v155 offset:15296
	s_waitcnt lgkmcnt(0)
	v_cvt_pk_bf16_f32 v149, v156, v157
	ds_read_b32 v156, v155 offset:96
	ds_read_b32 v157, v155 offset:2272
	global_store_dwordx4 v158, v[146:149], s[22:23]
	s_add_u32 s22, s22, s12
	s_addc_u32 s23, s23, s13
	s_waitcnt lgkmcnt(0)
	v_cvt_pk_bf16_f32 v146, v156, v157
	ds_read_b32 v148, v155 offset:4448
	ds_read_b32 v149, v155 offset:6624
	s_waitcnt lgkmcnt(0)
	v_cvt_pk_bf16_f32 v147, v148, v149
	ds_read_b32 v148, v155 offset:8800
	ds_read_b32 v149, v155 offset:10976
	s_waitcnt lgkmcnt(0)
	v_cvt_pk_bf16_f32 v148, v148, v149
	ds_read_b32 v156, v155 offset:13152
	ds_read_b32 v157, v155 offset:15328
	s_waitcnt lgkmcnt(0)
	v_cvt_pk_bf16_f32 v149, v156, v157
	ds_read_b32 v156, v155 offset:128
	ds_read_b32 v157, v155 offset:2304
	global_store_dwordx4 v158, v[146:149], s[22:23]
	s_add_u32 s22, s22, s12
	s_addc_u32 s23, s23, s13
	s_waitcnt lgkmcnt(0)
	v_cvt_pk_bf16_f32 v146, v156, v157
	ds_read_b32 v148, v155 offset:4480
	ds_read_b32 v149, v155 offset:6656
	s_waitcnt lgkmcnt(0)
	v_cvt_pk_bf16_f32 v147, v148, v149
	ds_read_b32 v148, v155 offset:8832
	ds_read_b32 v149, v155 offset:11008
	s_waitcnt lgkmcnt(0)
	v_cvt_pk_bf16_f32 v148, v148, v149
	ds_read_b32 v156, v155 offset:13184
	ds_read_b32 v157, v155 offset:15360
	s_waitcnt lgkmcnt(0)
	v_cvt_pk_bf16_f32 v149, v156, v157
	ds_read_b32 v156, v155 offset:160
	ds_read_b32 v157, v155 offset:2336
	global_store_dwordx4 v158, v[146:149], s[22:23]
	s_waitcnt lgkmcnt(0)
	v_cvt_pk_bf16_f32 v176, v156, v157
	ds_read_b32 v146, v155 offset:4512
	ds_read_b32 v147, v155 offset:6688
	s_waitcnt lgkmcnt(0)
	v_cvt_pk_bf16_f32 v177, v146, v147
	ds_read_b32 v146, v155 offset:8864
	ds_read_b32 v147, v155 offset:11040
	s_waitcnt lgkmcnt(0)
	v_cvt_pk_bf16_f32 v178, v146, v147
	v_add_u32_e32 v146, 0x600, v155
	ds_read_b32 v148, v155 offset:13216
	ds_read_b32 v149, v155 offset:15392
	s_add_u32 s22, s22, s12
	s_waitcnt lgkmcnt(0)
	v_cvt_pk_bf16_f32 v179, v148, v149
	ds_read_b32 v148, v155 offset:192
	ds_read_b32 v149, v155 offset:2368
	s_addc_u32 s23, s23, s13
	global_store_dwordx4 v158, v[176:179], s[22:23]
	s_add_u32 s22, s22, s12
	s_addc_u32 s23, s23, s13
	s_waitcnt lgkmcnt(0)
	v_cvt_pk_bf16_f32 v176, v148, v149
	ds_read_b32 v148, v155 offset:4544
	ds_read_b32 v149, v155 offset:6720
	s_waitcnt lgkmcnt(0)
	v_cvt_pk_bf16_f32 v177, v148, v149
	ds_read_b32 v148, v155 offset:8896
	ds_read_b32 v149, v155 offset:11072
	s_waitcnt lgkmcnt(0)
	v_cvt_pk_bf16_f32 v178, v148, v149
	ds_read_b32 v148, v155 offset:13248
	ds_read_b32 v149, v155 offset:15424
	s_waitcnt lgkmcnt(0)
	v_cvt_pk_bf16_f32 v179, v148, v149
	ds_read_b32 v148, v155 offset:224
	ds_read_b32 v149, v155 offset:2400
	v_add_u32_e32 v147, 0x200, v155
	global_store_dwordx4 v158, v[176:179], s[22:23]
	s_add_u32 s12, s22, s12
	s_addc_u32 s13, s23, s13
	s_waitcnt lgkmcnt(0)
	v_cvt_pk_bf16_f32 v176, v148, v149
	ds_read_b32 v148, v155 offset:4576
	ds_read_b32 v149, v155 offset:6752
	s_waitcnt lgkmcnt(0)
	v_cvt_pk_bf16_f32 v177, v148, v149
	ds_read_b32 v148, v155 offset:8928
	ds_read_b32 v149, v155 offset:11104
	s_waitcnt lgkmcnt(0)
	v_cvt_pk_bf16_f32 v178, v148, v149
	ds_read_b32 v148, v155 offset:13280
	ds_read_b32 v149, v155 offset:15456
	s_waitcnt lgkmcnt(0)
	v_cvt_pk_bf16_f32 v179, v148, v149
	global_store_dwordx4 v158, v[176:179], s[12:13]
	s_waitcnt lgkmcnt(0)
	s_cmp_gt_u32 s28, 13
	s_cselect_b64 s[12:13], -1, 0
	s_and_b64 vcc, exec, s[12:13]
	s_cbranch_vccnz .LBB0_294
	s_add_i32 s11, s24, 0xffff1000
	s_cmpk_gt_i32 s11, 0xfff
	s_mov_b64 s[22:23], -1
	s_cbranch_scc0 .LBB0_326
	s_cmpk_gt_u32 s11, 0x1fff
	s_cbranch_scc0 .LBB0_323
	s_cmpk_gt_u32 s11, 0x2fff
	s_cbranch_scc0 .LBB0_320
	s_add_i32 s0, s25, 0x400
	s_and_b32 s29, s0, 0xfc0
	s_cmpk_gt_u32 s11, 0x3fff
	s_cbranch_scc0 .LBB0_317
	s_and_b32 s0, s11, 0x7fffffc0
	s_addk_i32 s0, 0xc000
	s_lshl_b64 s[6:7], s[0:1], 14
	v_lshl_add_u64 v[2:3], v[142:143], 0, s[6:7]
	s_lshl_b32 s6, s29, 2
	s_mov_b32 s7, s1
	v_lshl_add_u64 v[2:3], v[2:3], 0, s[6:7]
	s_lshl_b32 s6, s29, 15
	v_readlane_b32 s22, v254, 13
	v_readlane_b32 s23, v254, 14
	s_add_u32 s22, s22, s6
	s_addc_u32 s23, s23, 0
	s_lshl_b64 s[6:7], s[0:1], 1
	s_add_u32 s6, s22, s6
	s_addc_u32 s7, s23, s7
	s_mov_b64 s[22:23], 0

; #define LAS __attribute__((address_space(3)))
; #define LDS_WAIT() asm volatile("s_waitcnt lgkmcnt(0)" ::: "memory")
; __device__ __forceinline__ void p0_load(const P0Item& it, f32x4 (&w)[16], int lane) {
;     const unsigned voff = (unsigned)(((lane >> 4) * it.ldw + (lane & 15) * 4) * 4);
; #pragma unroll
;     for (int i = 0; i < 16; ++i) w[i] = __builtin_nontemporal_load((const f32x4*)((const char*)(it.src + (size_t)(4 * i) * it.ldw) + voff));
; }
; __device__ __forceinline__ void p0_finish(const P0Item& it, const f32x4 (&w)[16], LAS float* scr, int lane) {
;     const int c4 = (lane & 15) * 4, kr = lane >> 4;
;     if (it.gain) { const unsigned goff = (unsigned)(kr * 4);
; #pragma unroll
;         for (int i = 0; i < 16; ++i) { const float g = *(const float*)((const char*)(it.gain + 4 * i) + goff); *(LAS f32x4*)(scr + (kr + 4 * i) * 68 + c4) = w[i] * g; } }
;     else {
; #pragma unroll
;         for (int i = 0; i < 16; ++i) *(LAS f32x4*)(scr + (kr + 4 * i) * 68 + c4) = w[i]; }
;     LDS_WAIT(); asm volatile("" ::: "memory");
;     const unsigned soff = (unsigned)(((lane >> 3) * it.K + 8 * (lane & 7)) * 2);
.LBB0_456:
	v_mov_b32_e32 v134, v182
	v_readlane_b32 s24, v254, 8
	s_mov_b32 s25, s2
	v_mov_b64_e32 v[2:3], s[92:93]
	flat_load_dwordx2 v[138:139], v[2:3] offset:120 sc0 sc1
	s_waitcnt vmcnt(0)
	s_lshl_b32 s0, s24, 8
	s_add_i32 s10, s0, s25
	s_ashr_i32 s0, s10, 31
	s_lshr_b32 s0, s0, 24
	s_add_i32 s0, s10, s0
	s_ashr_i32 s1, s0, 8
	s_and_b32 s0, s0, 0x3ffff00
	s_sub_i32 s4, s10, s0
	s_lshl_b32 s0, s1, 6
	s_ashr_i32 s1, s0, 31
	flat_load_dwordx2 v[142:143], v[2:3] offset:112 sc0 sc1
	s_waitcnt vmcnt(0)
	v_lshlrev_b32_e32 v2, 4, v134
	s_lshl_b32 s8, s4, 6
	s_lshl_b64 s[4:5], s[0:1], 16
	v_ashrrev_i32_e32 v150, 4, v134
	v_and_b32_e32 v155, 0xf0, v2
	s_ashr_i32 s9, s8, 31
	v_mov_b32_e32 v141, 0
	v_lshl_or_b32 v140, v150, 16, v155
	s_mov_b32 s26, 0x40000
	s_mov_b32 s27, 0x80000
	s_mov_b32 s28, 0xc0000
	s_mov_b32 s29, 0x100000
	s_mov_b32 s30, 0x140000
	s_mov_b32 s31, 0x180000
	s_mov_b32 s34, 0x1c0000
	s_mov_b32 s35, 0x200000
	s_mov_b32 s36, 0x240000
	s_mov_b32 s37, 0x280000
	s_mov_b32 s38, 0x2c0000
	s_mov_b32 s39, 0x300000
	v_ashrrev_i32_e32 v152, 3, v134
	v_lshlrev_b32_e32 v136, 2, v150
	v_mov_b32_e32 v137, v141
	s_mov_b32 s40, 0
	v_mov_b32_e32 v145, v141
	s_mov_b32 s42, 0x10000
	s_mov_b32 s43, 0x20000
	s_mov_b32 s44, 0x30000
	s_mov_b32 s45, 0x50000
	s_mov_b32 s46, 0x60000
	s_waitcnt lgkmcnt(0)
	v_lshl_add_u64 v[2:3], v[138:139], 0, s[4:5]
	v_lshl_add_u64 v[2:3], s[8:9], 2, v[2:3]
	v_lshl_add_u64 v[58:59], v[2:3], 0, v[140:141]
	v_add_co_u32_e32 v6, vcc, s26, v58
	s_mov_b32 s4, 0x340000
	s_nop 0
	v_addc_co_u32_e32 v7, vcc, 0, v59, vcc
	v_add_co_u32_e32 v10, vcc, s27, v58
	s_lshl_b64 s[8:9], s[8:9], 13
	s_nop 0
	v_addc_co_u32_e32 v11, vcc, 0, v59, vcc
	v_add_co_u32_e32 v14, vcc, s28, v58
	v_lshl_add_u64 v[66:67], s[0:1], 2, v[142:143]
	s_nop 0
	v_addc_co_u32_e32 v15, vcc, 0, v59, vcc
	v_add_co_u32_e32 v18, vcc, s29, v58
	v_cmp_eq_u64_e64 s[6:7], 0, v[142:143]
	s_nop 0
	v_addc_co_u32_e32 v19, vcc, 0, v59, vcc
	v_add_co_u32_e32 v22, vcc, s30, v58
	v_cndmask_b32_e64 v148, v66, 0, s[6:7]
	s_nop 0
	v_addc_co_u32_e32 v23, vcc, 0, v59, vcc
	v_add_co_u32_e32 v26, vcc, s31, v58
	v_cndmask_b32_e64 v149, v67, 0, s[6:7]
	s_nop 0
	v_addc_co_u32_e32 v27, vcc, 0, v59, vcc
	v_add_co_u32_e32 v30, vcc, s34, v58
	v_lshlrev_b32_e32 v67, 2, v152
	s_nop 0
	v_addc_co_u32_e32 v31, vcc, 0, v59, vcc
	v_add_co_u32_e32 v34, vcc, s35, v58
	v_lshl_add_u64 v[146:147], v[142:143], 0, v[136:137]
	s_nop 0
	v_addc_co_u32_e32 v35, vcc, 0, v59, vcc
	v_add_co_u32_e32 v38, vcc, s36, v58
	s_nop 1
	v_addc_co_u32_e32 v39, vcc, 0, v59, vcc
	v_add_co_u32_e32 v42, vcc, s37, v58
	flat_load_dwordx4 v[2:5], v[58:59] nt
	s_nop 0
	flat_load_dwordx4 v[6:9], v[6:7] nt
	s_nop 0
	flat_load_dwordx4 v[10:13], v[10:11] nt
	s_nop 0
	flat_load_dwordx4 v[14:17], v[14:15] nt
	s_nop 0
	flat_load_dwordx4 v[18:21], v[18:19] nt
	s_nop 0
	flat_load_dwordx4 v[22:25], v[22:23] nt
	s_nop 0
	flat_load_dwordx4 v[26:29], v[26:27] nt
	s_nop 0
	flat_load_dwordx4 v[30:33], v[30:31] nt
	s_nop 0
	flat_load_dwordx4 v[34:37], v[34:35] nt
	s_nop 0
	flat_load_dwordx4 v[38:41], v[38:39] nt
	v_addc_co_u32_e32 v43, vcc, 0, v59, vcc
	v_add_co_u32_e32 v46, vcc, s38, v58
	s_nop 1
	v_addc_co_u32_e32 v47, vcc, 0, v59, vcc
	v_add_co_u32_e32 v50, vcc, s39, v58
	flat_load_dwordx4 v[42:45], v[42:43] nt
	s_nop 0
	flat_load_dwordx4 v[46:49], v[46:47] nt
	v_addc_co_u32_e32 v51, vcc, 0, v59, vcc
	v_add_co_u32_e32 v54, vcc, s4, v58
	s_mov_b32 s4, 0x380000
	s_nop 0
	v_addc_co_u32_e32 v55, vcc, 0, v59, vcc
	v_add_co_u32_e32 v60, vcc, s4, v58
	s_mov_b32 s4, 0x3c0000
	s_nop 0
	v_addc_co_u32_e32 v61, vcc, 0, v59, vcc
	v_add_co_u32_e32 v62, vcc, s4, v58
	flat_load_dwordx4 v[50:53], v[50:51] nt
	s_nop 0
	flat_load_dwordx4 v[54:57], v[54:55] nt
	v_addc_co_u32_e32 v63, vcc, 0, v59, vcc
	flat_load_dwordx4 v[58:61], v[60:61] nt
	s_nop 0
	flat_load_dwordx4 v[62:65], v[62:63] nt
	s_mul_i32 s4, s24, 0x4400
	s_add_i32 s11, s4, 0
	s_add_u32 s8, s33, s8
	s_addc_u32 s9, s60, s9
	s_lshl_b64 s[0:1], s[0:1], 1
	s_add_u32 s0, s8, s0
	s_movk_i32 s8, 0x110
	v_mul_lo_u32 v66, v150, s8
	v_add3_u32 v151, s11, v155, v66
	v_mul_u32_u24_e32 v248, 0x770, v150
	v_add_u32_e32 v151, v151, v248
	v_lshlrev_b32_e32 v66, 3, v134
	v_and_b32_e32 v153, 56, v66
	v_lshlrev_b32_e32 v66, 13, v152
	v_lshl_or_b32 v144, v153, 1, v66
	v_mul_u32_u24_e32 v66, 0x110, v153
	v_cmp_ne_u64_e64 s[4:5], 0, v[142:143]
	s_addc_u32 s1, s9, s1
	v_add3_u32 v154, s11, v66, v67
	v_mul_u32_u24_e32 v248, 238, v153
	v_sub_u32_e32 v154, v154, v248
	s_add_i32 s41, s10, 0x1000
	s_branch .LBB0_458
; #define GAS __attribute__((address_space(1)))
; #define LAS __attribute__((address_space(3)))
; __device__ __forceinline__ unsigned cvt_pk_bf16(float lo, float hi) { unsigned r; asm volatile("v_cvt_pk_bf16_f32 %0, %1, %2" : "=v"(r) : "v"(lo), "v"(hi)); return r; }
; #define LDS_WAIT() asm volatile("s_waitcnt lgkmcnt(0)" ::: "memory")
; __device__ __forceinline__ void p0_finish(const P0Item& it, const f32x4 (&w)[16], LAS float* scr, int lane) {
;     ...
;         for (int i = 0; i < 16; ++i) *(LAS f32x4*)(scr + (kr + 4 * i) * 68 + c4) = w[i]; }
;     LDS_WAIT(); asm volatile("" ::: "memory");
;     const unsigned soff = (unsigned)(((lane >> 3) * it.K + 8 * (lane & 7)) * 2);
; #pragma unroll
;     for (int j = 0; j < 8; ++j) { const int n = (lane >> 3) + 8 * j, c = lane & 7; const LAS float* sp = scr + (8 * c) * 68 + n;
;         u32x4 o; o.x = cvt_pk_bf16(sp[0 * 68], sp[1 * 68]); o.y = cvt_pk_bf16(sp[2 * 68], sp[3 * 68]); o.z = cvt_pk_bf16(sp[4 * 68], sp[5 * 68]); o.w = cvt_pk_bf16(sp[6 * 68], sp[7 * 68]);
;         *(GAS u32x4*)((char*)(it.dst + (size_t)(8 * j) * it.K) + soff) = o; }
;     LDS_WAIT(); asm volatile("" ::: "memory");
.LBB0_457:
	s_or_b64 exec, exec, s[22:23]
	s_waitcnt vmcnt(0)
	ds_write_b128 v151, v[66:69] offset:10608
	s_waitcnt lgkmcnt(0)
	s_lshl_b64 s[10:11], s[10:11], 13
	s_add_u32 s10, s33, s10
	ds_read_b32 v66, v154
	ds_read_b32 v67, v154 offset:2176
	s_addc_u32 s11, s60, s11
	s_lshl_b64 s[8:9], s[8:9], 1
	s_waitcnt lgkmcnt(0)
	v_cvt_pk_bf16_f32 v66, v66, v67
	ds_read_b32 v68, v154 offset:4352
	ds_read_b32 v69, v154 offset:6528
	s_add_u32 s8, s10, s8
	s_waitcnt lgkmcnt(0)
	v_cvt_pk_bf16_f32 v67, v68, v69
	ds_read_b32 v68, v154 offset:8704
	ds_read_b32 v69, v154 offset:10880
	s_addc_u32 s9, s11, s9
	s_waitcnt lgkmcnt(0)
	v_cvt_pk_bf16_f32 v68, v68, v69
	ds_read_b32 v70, v154 offset:13056
	ds_read_b32 v71, v154 offset:15232
	s_waitcnt lgkmcnt(0)
	v_cvt_pk_bf16_f32 v69, v70, v71
	v_lshl_add_u64 v[72:73], s[8:9], 0, v[144:145]
	ds_read_b32 v70, v154 offset:32
	ds_read_b32 v71, v154 offset:2208
	global_store_dwordx4 v[72:73], v[66:69], off
	v_add_co_u32_e32 v74, vcc, s42, v72
	s_waitcnt lgkmcnt(0)
	v_cvt_pk_bf16_f32 v66, v70, v71
	ds_read_b32 v68, v154 offset:4384
	ds_read_b32 v69, v154 offset:6560
	s_waitcnt lgkmcnt(0)
	v_cvt_pk_bf16_f32 v67, v68, v69
	ds_read_b32 v68, v154 offset:8736
	ds_read_b32 v69, v154 offset:10912
	s_waitcnt lgkmcnt(0)
	v_cvt_pk_bf16_f32 v68, v68, v69
	ds_read_b32 v70, v154 offset:13088
	ds_read_b32 v71, v154 offset:15264
	s_waitcnt lgkmcnt(0)
	v_cvt_pk_bf16_f32 v69, v70, v71
	v_addc_co_u32_e32 v75, vcc, 0, v73, vcc
	ds_read_b32 v70, v154 offset:64
	ds_read_b32 v71, v154 offset:2240
	global_store_dwordx4 v[74:75], v[66:69], off
	v_add_co_u32_e32 v74, vcc, s43, v72
	s_waitcnt lgkmcnt(0)
	v_cvt_pk_bf16_f32 v66, v70, v71
	ds_read_b32 v68, v154 offset:4416
	ds_read_b32 v69, v154 offset:6592
	s_waitcnt lgkmcnt(0)
	v_cvt_pk_bf16_f32 v67, v68, v69
	ds_read_b32 v68, v154 offset:8768
	ds_read_b32 v69, v154 offset:10944
	s_waitcnt lgkmcnt(0)
	v_cvt_pk_bf16_f32 v68, v68, v69
	ds_read_b32 v70, v154 offset:13120
	ds_read_b32 v71, v154 offset:15296
	s_waitcnt lgkmcnt(0)
	v_cvt_pk_bf16_f32 v69, v70, v71
	v_addc_co_u32_e32 v75, vcc, 0, v73, vcc
	ds_read_b32 v70, v154 offset:96
	ds_read_b32 v71, v154 offset:2272
	global_store_dwordx4 v[74:75], v[66:69], off
	v_add_co_u32_e32 v74, vcc, s44, v72
	s_waitcnt lgkmcnt(0)
	v_cvt_pk_bf16_f32 v66, v70, v71
	ds_read_b32 v68, v154 offset:4448
	ds_read_b32 v69, v154 offset:6624
	s_waitcnt lgkmcnt(0)
	v_cvt_pk_bf16_f32 v67, v68, v69
	ds_read_b32 v68, v154 offset:8800
	ds_read_b32 v69, v154 offset:10976
	s_waitcnt lgkmcnt(0)
	v_cvt_pk_bf16_f32 v68, v68, v69
	ds_read_b32 v70, v154 offset:13152
	ds_read_b32 v71, v154 offset:15328
	s_waitcnt lgkmcnt(0)
	v_cvt_pk_bf16_f32 v69, v70, v71
	v_addc_co_u32_e32 v75, vcc, 0, v73, vcc
	ds_read_b32 v70, v154 offset:128
	ds_read_b32 v71, v154 offset:2304
	global_store_dwordx4 v[74:75], v[66:69], off
	v_add_co_u32_e32 v74, vcc, s26, v72
	s_waitcnt lgkmcnt(0)
	v_cvt_pk_bf16_f32 v66, v70, v71
	ds_read_b32 v68, v154 offset:4480
	ds_read_b32 v69, v154 offset:6656
	s_waitcnt lgkmcnt(0)
	v_cvt_pk_bf16_f32 v67, v68, v69
	ds_read_b32 v68, v154 offset:8832
	ds_read_b32 v69, v154 offset:11008
	s_waitcnt lgkmcnt(0)
	v_cvt_pk_bf16_f32 v68, v68, v69
	ds_read_b32 v70, v154 offset:13184
	ds_read_b32 v71, v154 offset:15360
	s_waitcnt lgkmcnt(0)
	v_cvt_pk_bf16_f32 v69, v70, v71
	v_addc_co_u32_e32 v75, vcc, 0, v73, vcc
	ds_read_b32 v70, v154 offset:160
	ds_read_b32 v71, v154 offset:2336
	global_store_dwordx4 v[74:75], v[66:69], off
	v_add_co_u32_e32 v74, vcc, s45, v72
	s_waitcnt lgkmcnt(0)
	v_cvt_pk_bf16_f32 v66, v70, v71
	ds_read_b32 v68, v154 offset:4512
	ds_read_b32 v69, v154 offset:6688
	s_waitcnt lgkmcnt(0)
	v_cvt_pk_bf16_f32 v67, v68, v69
	ds_read_b32 v68, v154 offset:8864
	ds_read_b32 v69, v154 offset:11040
	s_waitcnt lgkmcnt(0)
	v_cvt_pk_bf16_f32 v68, v68, v69
	ds_read_b32 v70, v154 offset:13216
	ds_read_b32 v71, v154 offset:15392
	s_waitcnt lgkmcnt(0)
	v_cvt_pk_bf16_f32 v69, v70, v71
	v_addc_co_u32_e32 v75, vcc, 0, v73, vcc
	ds_read_b32 v70, v154 offset:192
	ds_read_b32 v71, v154 offset:2368
	global_store_dwordx4 v[74:75], v[66:69], off
	v_add_co_u32_e32 v74, vcc, s46, v72
	s_waitcnt lgkmcnt(0)
	v_cvt_pk_bf16_f32 v66, v70, v71
	ds_read_b32 v68, v154 offset:4544
	ds_read_b32 v69, v154 offset:6720
	s_waitcnt lgkmcnt(0)
	v_cvt_pk_bf16_f32 v67, v68, v69
	ds_read_b32 v68, v154 offset:8896
	ds_read_b32 v69, v154 offset:11072
	s_waitcnt lgkmcnt(0)
	v_cvt_pk_bf16_f32 v68, v68, v69
	ds_read_b32 v70, v154 offset:13248
	ds_read_b32 v71, v154 offset:15424
	s_waitcnt lgkmcnt(0)
	v_cvt_pk_bf16_f32 v69, v70, v71
	v_addc_co_u32_e32 v75, vcc, 0, v73, vcc
	ds_read_b32 v70, v154 offset:224
	ds_read_b32 v71, v154 offset:2400
	global_store_dwordx4 v[74:75], v[66:69], off
	v_add_co_u32_e32 v72, vcc, 0x70000, v72
	s_waitcnt lgkmcnt(0)
	v_cvt_pk_bf16_f32 v66, v70, v71
	ds_read_b32 v68, v154 offset:4576
	ds_read_b32 v69, v154 offset:6752
	s_waitcnt lgkmcnt(0)
	v_cvt_pk_bf16_f32 v67, v68, v69
	ds_read_b32 v68, v154 offset:8928
	ds_read_b32 v69, v154 offset:11104
	v_addc_co_u32_e32 v73, vcc, 0, v73, vcc
	s_waitcnt lgkmcnt(0)
	v_cvt_pk_bf16_f32 v68, v68, v69
	ds_read_b32 v70, v154 offset:13280
	ds_read_b32 v71, v154 offset:15456
	s_waitcnt lgkmcnt(0)
	v_cvt_pk_bf16_f32 v69, v70, v71
	global_store_dwordx4 v[72:73], v[66:69], off
	s_waitcnt lgkmcnt(0)
	s_add_i32 s40, s40, 2
	s_andn2_b64 vcc, exec, s[12:13]
	s_addk_i32 s41, 0x1000
	s_cbranch_vccz .LBB0_468
; #define LAS __attribute__((address_space(3)))
; __device__ __forceinline__ void p0_load(const P0Item& it, f32x4 (&w)[16], int lane) {
;     const unsigned voff = (unsigned)(((lane >> 4) * it.ldw + (lane & 15) * 4) * 4);
; #pragma unroll
;     for (int i = 0; i < 16; ++i) w[i] = __builtin_nontemporal_load((const f32x4*)((const char*)(it.src + (size_t)(4 * i) * it.ldw) + voff));
; }
; __device__ __forceinline__ void p0_finish(const P0Item& it, const f32x4 (&w)[16], LAS float* scr, int lane) {
;     const int c4 = (lane & 15) * 4, kr = lane >> 4;
;     if (it.gain) { const unsigned goff = (unsigned)(kr * 4);
; #pragma unroll
;         for (int i = 0; i < 16; ++i) { const float g = *(const float*)((const char*)(it.gain + 4 * i) + goff); *(LAS f32x4*)(scr + (kr + 4 * i) * 68 + c4) = w[i] * g; } }
.LBB0_458:
	s_add_i32 s8, s41, 0xfffff800
	s_ashr_i32 s9, s8, 31
	s_lshr_b32 s9, s9, 24
	s_add_i32 s9, s8, s9
	s_ashr_i32 s10, s9, 8
	s_and_b32 s9, s9, 0x3ffff00
	s_sub_i32 s9, s8, s9
	s_lshl_b32 s8, s10, 6
	s_lshl_b32 s10, s9, 6
	s_ashr_i32 s9, s8, 31
	s_lshl_b64 s[12:13], s[8:9], 16
	v_lshl_add_u64 v[66:67], v[138:139], 0, s[12:13]
	s_ashr_i32 s11, s10, 31
	v_lshl_add_u64 v[66:67], s[10:11], 2, v[66:67]
	v_lshl_add_u64 v[66:67], v[66:67], 0, v[140:141]
	v_add_co_u32_e32 v68, vcc, s26, v66
	s_nop 1
	v_addc_co_u32_e32 v69, vcc, 0, v67, vcc
	flat_load_dwordx4 v[126:129], v[66:67] nt
	flat_load_dwordx4 v[122:125], v[68:69] nt
	v_add_co_u32_e32 v68, vcc, s27, v66
	s_nop 1
	v_addc_co_u32_e32 v69, vcc, 0, v67, vcc
	v_add_co_u32_e32 v70, vcc, s28, v66
	s_nop 1
	v_addc_co_u32_e32 v71, vcc, 0, v67, vcc
	flat_load_dwordx4 v[118:121], v[68:69] nt
	flat_load_dwordx4 v[114:117], v[70:71] nt
	v_add_co_u32_e32 v68, vcc, s29, v66
	s_nop 1
	v_addc_co_u32_e32 v69, vcc, 0, v67, vcc
	v_add_co_u32_e32 v70, vcc, s30, v66
	s_nop 1
	v_addc_co_u32_e32 v71, vcc, 0, v67, vcc
	flat_load_dwordx4 v[110:113], v[68:69] nt
	flat_load_dwordx4 v[106:109], v[70:71] nt
	v_add_co_u32_e32 v68, vcc, s31, v66
	s_nop 1
	v_addc_co_u32_e32 v69, vcc, 0, v67, vcc
	v_add_co_u32_e32 v70, vcc, s34, v66
	s_nop 1
	v_addc_co_u32_e32 v71, vcc, 0, v67, vcc
	flat_load_dwordx4 v[102:105], v[68:69] nt
	flat_load_dwordx4 v[98:101], v[70:71] nt
	v_add_co_u32_e32 v68, vcc, s35, v66
	s_nop 1
	v_addc_co_u32_e32 v69, vcc, 0, v67, vcc
	v_add_co_u32_e32 v70, vcc, s36, v66
	s_nop 1
	v_addc_co_u32_e32 v71, vcc, 0, v67, vcc
	flat_load_dwordx4 v[94:97], v[68:69] nt
	flat_load_dwordx4 v[90:93], v[70:71] nt
	v_add_co_u32_e32 v68, vcc, s37, v66
	s_nop 1
	v_addc_co_u32_e32 v69, vcc, 0, v67, vcc
	v_add_co_u32_e32 v70, vcc, s38, v66
	s_nop 1
	v_addc_co_u32_e32 v71, vcc, 0, v67, vcc
	flat_load_dwordx4 v[86:89], v[68:69] nt
	flat_load_dwordx4 v[82:85], v[70:71] nt
	v_add_co_u32_e32 v68, vcc, s39, v66
	s_nop 1
	v_addc_co_u32_e32 v69, vcc, 0, v67, vcc
	v_add_co_u32_e32 v70, vcc, 0x340000, v66
	s_nop 1
	v_addc_co_u32_e32 v71, vcc, 0, v67, vcc
	flat_load_dwordx4 v[78:81], v[68:69] nt
	flat_load_dwordx4 v[74:77], v[70:71] nt
	v_add_co_u32_e32 v68, vcc, 0x380000, v66
	s_nop 1
	v_addc_co_u32_e32 v69, vcc, 0, v67, vcc
	v_add_co_u32_e32 v66, vcc, 0x3c0000, v66
	s_nop 1
	v_addc_co_u32_e32 v67, vcc, 0, v67, vcc
	flat_load_dwordx4 v[70:73], v[68:69] nt
	s_nop 0
	flat_load_dwordx4 v[66:69], v[66:67] nt
	v_cmp_ne_u64_e32 vcc, 0, v[148:149]
	s_and_saveexec_b64 s[12:13], vcc
	s_xor_b64 s[12:13], exec, s[12:13]
	s_cbranch_execz .LBB0_460
	v_lshl_add_u64 v[156:157], v[148:149], 0, v[136:137]
	global_load_dword v248, v[156:157], off
	global_load_dword v249, v[156:157], off offset:16
	global_load_dword v250, v[156:157], off offset:32
	global_load_dword v251, v[156:157], off offset:48
	global_load_dword v252, v[156:157], off offset:64
	global_load_dword v253, v[156:157], off offset:80
	s_waitcnt vmcnt(0) lgkmcnt(0)
	v_pk_mul_f32 v[132:133], v[4:5], v[248:249] op_sel_hi:[1,0]
	v_pk_mul_f32 v[130:131], v[2:3], v[248:249] op_sel_hi:[1,0]
	ds_write_b128 v151, v[130:133]
	s_nop 1
	v_pk_mul_f32 v[132:133], v[8:9], v[248:249] op_sel:[0,1]
	v_pk_mul_f32 v[130:131], v[6:7], v[248:249] op_sel:[0,1]
	ds_write_b128 v151, v[130:133] offset:8704
	s_nop 1
	v_pk_mul_f32 v[132:133], v[12:13], v[250:251] op_sel_hi:[1,0]
	v_pk_mul_f32 v[130:131], v[10:11], v[250:251] op_sel_hi:[1,0]
	ds_write_b128 v151, v[130:133] offset:272
	s_nop 1
	v_pk_mul_f32 v[132:133], v[16:17], v[250:251] op_sel:[0,1]
	v_pk_mul_f32 v[130:131], v[14:15], v[250:251] op_sel:[0,1]
	ds_write_b128 v151, v[130:133] offset:8976
	s_nop 1
	v_pk_mul_f32 v[132:133], v[20:21], v[252:253] op_sel_hi:[1,0]
	v_pk_mul_f32 v[130:131], v[18:19], v[252:253] op_sel_hi:[1,0]
	ds_write_b128 v151, v[130:133] offset:544
	s_nop 1
	v_pk_mul_f32 v[132:133], v[24:25], v[252:253] op_sel:[0,1]
	v_pk_mul_f32 v[130:131], v[22:23], v[252:253] op_sel:[0,1]
	ds_write_b128 v151, v[130:133] offset:9248
	s_nop 1
	global_load_dword v248, v[156:157], off offset:96
	global_load_dword v249, v[156:157], off offset:112
	global_load_dword v250, v[156:157], off offset:128
	global_load_dword v251, v[156:157], off offset:144
	global_load_dword v252, v[156:157], off offset:160
	global_load_dword v253, v[156:157], off offset:176
	s_waitcnt vmcnt(0) lgkmcnt(0)
	v_pk_mul_f32 v[132:133], v[28:29], v[248:249] op_sel_hi:[1,0]
	v_pk_mul_f32 v[130:131], v[26:27], v[248:249] op_sel_hi:[1,0]
	ds_write_b128 v151, v[130:133] offset:816
	s_nop 1
	v_pk_mul_f32 v[132:133], v[32:33], v[248:249] op_sel:[0,1]
	v_pk_mul_f32 v[130:131], v[30:31], v[248:249] op_sel:[0,1]
	ds_write_b128 v151, v[130:133] offset:9520
	s_nop 1
	v_pk_mul_f32 v[132:133], v[36:37], v[250:251] op_sel_hi:[1,0]
	v_pk_mul_f32 v[130:131], v[34:35], v[250:251] op_sel_hi:[1,0]
	ds_write_b128 v151, v[130:133] offset:1088
	s_nop 1
	v_pk_mul_f32 v[132:133], v[40:41], v[250:251] op_sel:[0,1]
	v_pk_mul_f32 v[130:131], v[38:39], v[250:251] op_sel:[0,1]
	ds_write_b128 v151, v[130:133] offset:9792
	s_nop 1
	v_pk_mul_f32 v[132:133], v[44:45], v[252:253] op_sel_hi:[1,0]
	v_pk_mul_f32 v[130:131], v[42:43], v[252:253] op_sel_hi:[1,0]
	ds_write_b128 v151, v[130:133] offset:1360
	s_nop 1
	v_pk_mul_f32 v[132:133], v[48:49], v[252:253] op_sel:[0,1]
	v_pk_mul_f32 v[130:131], v[46:47], v[252:253] op_sel:[0,1]
	ds_write_b128 v151, v[130:133] offset:10064
	s_nop 1
	global_load_dword v248, v[156:157], off offset:192
	global_load_dword v249, v[156:157], off offset:208
	global_load_dword v250, v[156:157], off offset:224
	global_load_dword v251, v[156:157], off offset:240
	s_waitcnt vmcnt(0) lgkmcnt(0)
	v_pk_mul_f32 v[132:133], v[52:53], v[248:249] op_sel_hi:[1,0]
	v_pk_mul_f32 v[130:131], v[50:51], v[248:249] op_sel_hi:[1,0]
	ds_write_b128 v151, v[130:133] offset:1632
	s_nop 1
	v_pk_mul_f32 v[132:133], v[56:57], v[248:249] op_sel:[0,1]
	v_pk_mul_f32 v[130:131], v[54:55], v[248:249] op_sel:[0,1]
	ds_write_b128 v151, v[130:133] offset:10336
	s_nop 1
	v_pk_mul_f32 v[132:133], v[60:61], v[250:251] op_sel_hi:[1,0]
	v_pk_mul_f32 v[130:131], v[58:59], v[250:251] op_sel_hi:[1,0]
	ds_write_b128 v151, v[130:133] offset:1904
	s_nop 1
	v_pk_mul_f32 v[132:133], v[64:65], v[250:251] op_sel:[0,1]
	v_pk_mul_f32 v[130:131], v[62:63], v[250:251] op_sel:[0,1]

; #define GAS __attribute__((address_space(1)))
; #define LAS __attribute__((address_space(3)))
; __device__ __forceinline__ unsigned cvt_pk_bf16(float lo, float hi) { unsigned r; asm volatile("v_cvt_pk_bf16_f32 %0, %1, %2" : "=v"(r) : "v"(lo), "v"(hi)); return r; }
; #define LDS_WAIT() asm volatile("s_waitcnt lgkmcnt(0)" ::: "memory")
; __device__ __forceinline__ void p0_finish(const P0Item& it, const f32x4 (&w)[16], LAS float* scr, int lane) {
;     ...
;     const unsigned soff = (unsigned)(((lane >> 3) * it.K + 8 * (lane & 7)) * 2);
; #pragma unroll
;     for (int j = 0; j < 8; ++j) { const int n = (lane >> 3) + 8 * j, c = lane & 7; const LAS float* sp = scr + (8 * c) * 68 + n;
;         u32x4 o; o.x = cvt_pk_bf16(sp[0 * 68], sp[1 * 68]); o.y = cvt_pk_bf16(sp[2 * 68], sp[3 * 68]); o.z = cvt_pk_bf16(sp[4 * 68], sp[5 * 68]); o.w = cvt_pk_bf16(sp[6 * 68], sp[7 * 68]);
;         *(GAS u32x4*)((char*)(it.dst + (size_t)(8 * j) * it.K) + soff) = o; }
;     LDS_WAIT(); asm volatile("" ::: "memory");
.LBB0_462:
	s_or_b64 exec, exec, s[12:13]
	ds_write_b128 v151, v[130:133] offset:10608
	s_waitcnt lgkmcnt(0)
	ds_read_b32 v130, v154
	ds_read_b32 v131, v154 offset:2176
	s_waitcnt lgkmcnt(0)
	v_cvt_pk_bf16_f32 v156, v130, v131
	ds_read_b32 v132, v154 offset:4352
	ds_read_b32 v133, v154 offset:6528
	v_add_u32_e32 v130, 0x400, v154
	s_waitcnt lgkmcnt(0)
	v_cvt_pk_bf16_f32 v157, v132, v133
	ds_read_b32 v132, v154 offset:8704
	ds_read_b32 v133, v154 offset:10880
	s_waitcnt lgkmcnt(0)
	v_cvt_pk_bf16_f32 v158, v132, v133
	ds_read_b32 v132, v154 offset:13056
	ds_read_b32 v133, v154 offset:15232
	s_waitcnt lgkmcnt(0)
	v_cvt_pk_bf16_f32 v159, v132, v133
	ds_read_b32 v132, v154 offset:32
	ds_read_b32 v133, v154 offset:2208
	v_lshl_add_u64 v[160:161], s[0:1], 0, v[144:145]
	global_store_dwordx4 v[160:161], v[156:159], off
	v_add_co_u32_e32 v162, vcc, s42, v160
	s_waitcnt lgkmcnt(0)
	v_cvt_pk_bf16_f32 v156, v132, v133
	ds_read_b32 v132, v154 offset:4384
	ds_read_b32 v133, v154 offset:6560
	s_waitcnt lgkmcnt(0)
	v_cvt_pk_bf16_f32 v157, v132, v133
	ds_read_b32 v132, v154 offset:8736
	ds_read_b32 v133, v154 offset:10912
	s_waitcnt lgkmcnt(0)
	v_cvt_pk_bf16_f32 v158, v132, v133
	ds_read_b32 v132, v154 offset:13088
	ds_read_b32 v133, v154 offset:15264
	s_waitcnt lgkmcnt(0)
	v_cvt_pk_bf16_f32 v159, v132, v133
	ds_read_b32 v132, v154 offset:64
	ds_read_b32 v133, v154 offset:2240
	v_addc_co_u32_e32 v163, vcc, 0, v161, vcc
	global_store_dwordx4 v[162:163], v[156:159], off
	v_add_co_u32_e32 v162, vcc, s43, v160
	s_waitcnt lgkmcnt(0)
	v_cvt_pk_bf16_f32 v156, v132, v133
	ds_read_b32 v132, v154 offset:4416
	ds_read_b32 v133, v154 offset:6592
	s_waitcnt lgkmcnt(0)
	v_cvt_pk_bf16_f32 v157, v132, v133
	ds_read_b32 v132, v154 offset:8768
	ds_read_b32 v133, v154 offset:10944
	s_waitcnt lgkmcnt(0)
	v_cvt_pk_bf16_f32 v158, v132, v133
	ds_read_b32 v132, v154 offset:13120
	ds_read_b32 v133, v154 offset:15296
	s_waitcnt lgkmcnt(0)
	v_cvt_pk_bf16_f32 v159, v132, v133
	ds_read_b32 v132, v154 offset:96
	ds_read_b32 v133, v154 offset:2272
	v_addc_co_u32_e32 v163, vcc, 0, v161, vcc
	global_store_dwordx4 v[162:163], v[156:159], off
	v_add_co_u32_e32 v162, vcc, s44, v160
	s_waitcnt lgkmcnt(0)
	v_cvt_pk_bf16_f32 v156, v132, v133
	ds_read_b32 v132, v154 offset:4448
	ds_read_b32 v133, v154 offset:6624
	s_waitcnt lgkmcnt(0)
	v_cvt_pk_bf16_f32 v157, v132, v133
	ds_read_b32 v132, v154 offset:8800
	ds_read_b32 v133, v154 offset:10976
	s_waitcnt lgkmcnt(0)
	v_cvt_pk_bf16_f32 v158, v132, v133
	ds_read_b32 v132, v154 offset:13152
	ds_read_b32 v133, v154 offset:15328
	s_waitcnt lgkmcnt(0)
	v_cvt_pk_bf16_f32 v159, v132, v133
	ds_read_b32 v132, v154 offset:128
	ds_read_b32 v133, v154 offset:2304
	v_addc_co_u32_e32 v163, vcc, 0, v161, vcc
	global_store_dwordx4 v[162:163], v[156:159], off
	v_add_co_u32_e32 v162, vcc, s26, v160
	s_waitcnt lgkmcnt(0)
	v_cvt_pk_bf16_f32 v156, v132, v133
	ds_read_b32 v132, v154 offset:4480
	ds_read_b32 v133, v154 offset:6656
	s_waitcnt lgkmcnt(0)
	v_cvt_pk_bf16_f32 v157, v132, v133
	ds_read_b32 v132, v154 offset:8832
	ds_read_b32 v133, v154 offset:11008
	s_waitcnt lgkmcnt(0)
	v_cvt_pk_bf16_f32 v158, v132, v133
	ds_read_b32 v132, v154 offset:13184
	ds_read_b32 v133, v154 offset:15360
	s_waitcnt lgkmcnt(0)
	v_cvt_pk_bf16_f32 v159, v132, v133
	ds_read_b32 v132, v154 offset:160
	ds_read_b32 v133, v154 offset:2336
	v_addc_co_u32_e32 v163, vcc, 0, v161, vcc
	global_store_dwordx4 v[162:163], v[156:159], off
	v_add_u32_e32 v131, 0x600, v154
	v_add_co_u32_e32 v162, vcc, s45, v160
	s_waitcnt lgkmcnt(0)
	v_cvt_pk_bf16_f32 v156, v132, v133
	ds_read_b32 v132, v154 offset:4512
	ds_read_b32 v133, v154 offset:6688
	s_waitcnt lgkmcnt(0)
	v_cvt_pk_bf16_f32 v157, v132, v133
	ds_read_b32 v132, v154 offset:8864
	ds_read_b32 v133, v154 offset:11040
	s_waitcnt lgkmcnt(0)
	v_cvt_pk_bf16_f32 v158, v132, v133
	ds_read_b32 v132, v154 offset:13216
	ds_read_b32 v133, v154 offset:15392
	s_waitcnt lgkmcnt(0)
	v_cvt_pk_bf16_f32 v159, v132, v133
	ds_read_b32 v132, v154 offset:192
	ds_read_b32 v133, v154 offset:2368
	v_addc_co_u32_e32 v163, vcc, 0, v161, vcc
	global_store_dwordx4 v[162:163], v[156:159], off
	v_add_co_u32_e32 v164, vcc, s46, v160
	s_waitcnt lgkmcnt(0)
	v_cvt_pk_bf16_f32 v156, v132, v133
	ds_read_b32 v132, v154 offset:4544
	ds_read_b32 v133, v154 offset:6720
	s_waitcnt lgkmcnt(0)
	v_cvt_pk_bf16_f32 v157, v132, v133
	ds_read_b32 v132, v154 offset:8896
	ds_read_b32 v133, v154 offset:11072
	s_waitcnt lgkmcnt(0)
	v_cvt_pk_bf16_f32 v158, v132, v133
	ds_read_b32 v162, v154 offset:13248
	ds_read_b32 v163, v154 offset:15424
	v_add_u32_e32 v132, 0x200, v154
	s_waitcnt lgkmcnt(0)
	v_cvt_pk_bf16_f32 v159, v162, v163
	v_addc_co_u32_e32 v165, vcc, 0, v161, vcc
	ds_read_b32 v162, v154 offset:224
	ds_read_b32 v163, v154 offset:2400
	global_store_dwordx4 v[164:165], v[156:159], off
	v_add_co_u32_e32 v160, vcc, 0x70000, v160
	s_waitcnt lgkmcnt(0)
	v_cvt_pk_bf16_f32 v156, v162, v163
	ds_read_b32 v158, v154 offset:4576
	ds_read_b32 v159, v154 offset:6752
	s_waitcnt lgkmcnt(0)
	v_cvt_pk_bf16_f32 v157, v158, v159
	ds_read_b32 v158, v154 offset:8928
	ds_read_b32 v159, v154 offset:11104
	v_addc_co_u32_e32 v161, vcc, 0, v161, vcc
	s_waitcnt lgkmcnt(0)
	v_cvt_pk_bf16_f32 v158, v158, v159
	ds_read_b32 v162, v154 offset:13280
	ds_read_b32 v163, v154 offset:15456
	s_waitcnt lgkmcnt(0)
	v_cvt_pk_bf16_f32 v159, v162, v163
	global_store_dwordx4 v[160:161], v[156:159], off
	s_waitcnt lgkmcnt(0)
	s_cmp_gt_u32 s40, 5
	s_cselect_b64 s[12:13], -1, 0
	s_and_b64 vcc, exec, s[12:13]
	s_cbranch_vccz .LBB0_465
	s_and_saveexec_b64 s[22:23], s[4:5]
	s_xor_b64 s[22:23], exec, s[22:23]
	s_cbranch_execnz .LBB0_466
